# dilated attention: pipelined work-queue atomic + counted waits so next-item K/V prefetch overlaps compute; GEMM k-loop without per-segment setprio flips
# speedup vs baseline: 1.0469x; 1.0138x over previous
; #define PG8_STAGE(bufoff, gbase, voff) do { _Pragma("unroll") for (int _i = 0; _i < 2; ++_i) \
;         __builtin_amdgcn_global_load_lds((const unsigned*)((const char*)(gbase) + (voff)[_i]), (LAS unsigned*)(lds + (bufoff) + ldsw + _i * 8192), 16, 0, 0); } while (0)
; #define PG8_LDA(dst, b, h) do { _Pragma("unroll") for (int m = 0; m < 4; ++m) _Pragma("unroll") for (int k = 0; k < 2; ++k) dst[m][k] = *(const LAS bf16x8*)(lds + PG8_SA(b, h) + aoff + m * 2048 + k * 1024); } while (0)
; #define PG8_LDB(dst, b, h) do { _Pragma("unroll") for (int n = 0; n < 2; ++n) _Pragma("unroll") for (int k = 0; k < 2; ++k) dst[n][k] = *(const LAS bf16x8*)(lds + PG8_SB(b, h) + boff + n * 2048 + k * 1024); } while (0)
; __device__ __forceinline__ void gemm_phase(LAS unsigned char* lds, const GemmDesc& g) {
;     ...
;         for (int t = 0; t < nt; t += 2) {
;             const bool last = (t == nt - 2);
;             const char* a1 = cA + (size_t)(t + 1) * kstep;
;             const char* a2 = last ? nA : cA + (size_t)(t + 2) * kstep; const char* b2 = last ? nB : cB + (size_t)(t + 2) * kstep;
;             const char* a3 = a2 + kstep; const char* b3 = b2 + kstep;
;             PG8_LDB(B0, 0, 0); PG8_SCHED; PG8_LDA(At, 0, 0); PG8_STAGE(PG8_SA(1, 1), a1 + hstepA, voffA);
;             PG8_WAIT_L(8); PG8_BAR; PG8_WAIT_L(0); PG8_MMA(0, 0, At, B0); PG8_BAR; PG8_SCHED;
;             PG8_LDB(B1, 0, 1); PG8_STAGE(PG8_SB(0, 0), b2, voffB);
;             PG8_BAR; PG8_WAIT_L(0); PG8_MMA(0, 1, At, B1); PG8_BAR;
;             PG8_LDA(At, 0, 1); PG8_STAGE(PG8_SA(0, 0), a2, voffA);
;             PG8_BAR; PG8_WAIT_L(0); PG8_MMA(1, 0, At, B0); PG8_BAR; PG8_SCHED;
;             PG8_STAGE(PG8_SB(0, 1), b2 + hstep, voffB);
;             PG8_WAIT_V(6); PG8_BAR; PG8_MMA(1, 1, At, B1); PG8_BAR;
;             PG8_LDB(B0, 1, 0); PG8_SCHED; PG8_LDA(At, 1, 0); PG8_STAGE(PG8_SA(0, 1), a2 + hstepA, voffA);
;             PG8_WAIT_L(8); PG8_BAR; PG8_WAIT_L(0); PG8_MMA(0, 0, At, B0); PG8_BAR; PG8_SCHED;
;             PG8_LDB(B1, 1, 1); PG8_STAGE(PG8_SB(1, 0), b3, voffB);
;             PG8_BAR; PG8_WAIT_L(0); PG8_MMA(0, 1, At, B1); PG8_BAR;
;             PG8_LDA(At, 1, 1); PG8_STAGE(PG8_SA(1, 0), a3, voffA);
;             PG8_BAR; PG8_WAIT_L(0); PG8_MMA(1, 0, At, B0); PG8_BAR; PG8_SCHED;
;             PG8_STAGE(PG8_SB(1, 1), b3 + hstep, voffB);
;             PG8_WAIT_V(6); PG8_BAR; PG8_MMA(1, 1, At, B1); PG8_BAR;
.LBB0_208:
	s_add_i32 s44, s40, 2
	s_add_u32 s42, s0, 0x80
	s_addc_u32 s41, s1, 0
	s_add_i32 s45, 0, 0x10000
	v_add_u32_e32 v144, s45, v200
	ds_read_b128 v[132:135], v144
	ds_read_b128 v[136:139], v144 offset:1024
	ds_read_b128 v[140:143], v144 offset:2048
	ds_read_b128 v[144:147], v144 offset:3072
	s_cmp_eq_u32 s63, s40
	s_cselect_b32 s40, s24, s42
	s_cselect_b32 s41, s25, s41
	s_cselect_b32 s43, s35, s18
	s_cselect_b32 s42, s34, s13
	v_lshl_add_u64 v[194:195], s[0:1], 0, v[174:175]
	s_add_i32 m0, s5, 0xc000
	ds_read_b128 v[148:151], v229
	ds_read_b128 v[152:155], v229 offset:1024
	ds_read_b128 v[156:159], v229 offset:2048
	ds_read_b128 v[160:163], v229 offset:3072
	ds_read_b128 v[178:181], v229 offset:4096
	ds_read_b128 v[182:185], v229 offset:5120
	ds_read_b128 v[186:189], v229 offset:6144
	ds_read_b128 v[190:193], v229 offset:7168
	global_load_lds_dwordx4 v[194:195], off
	v_lshl_add_u64 v[194:195], s[0:1], 0, v[176:177]
	s_add_i32 m0, s5, 0xe000
	s_nop 0
	global_load_lds_dwordx4 v[194:195], off
	s_waitcnt lgkmcnt(8)
	s_barrier
	s_waitcnt lgkmcnt(0)
	s_waitcnt lgkmcnt(0)
	v_mfma_f32_16x16x32_bf16 v[128:131], v[132:135], v[148:151], v[128:131]
	v_mfma_f32_16x16x32_bf16 v[64:67], v[140:143], v[148:151], v[64:67]
	v_mfma_f32_16x16x32_bf16 v[120:123], v[132:135], v[156:159], v[120:123]
	v_mfma_f32_16x16x32_bf16 v[56:59], v[140:143], v[156:159], v[56:59]
	v_mfma_f32_16x16x32_bf16 v[112:115], v[132:135], v[178:181], v[112:115]
	v_mfma_f32_16x16x32_bf16 v[48:51], v[140:143], v[178:181], v[48:51]
	v_mfma_f32_16x16x32_bf16 v[104:107], v[132:135], v[186:189], v[104:107]
	v_mfma_f32_16x16x32_bf16 v[40:43], v[140:143], v[186:189], v[40:43]
	v_mfma_f32_16x16x32_bf16 v[128:131], v[136:139], v[152:155], v[128:131]
	v_mfma_f32_16x16x32_bf16 v[64:67], v[144:147], v[152:155], v[64:67]
	v_mfma_f32_16x16x32_bf16 v[120:123], v[136:139], v[160:163], v[120:123]
	v_mfma_f32_16x16x32_bf16 v[56:59], v[144:147], v[160:163], v[56:59]
	v_mfma_f32_16x16x32_bf16 v[112:115], v[136:139], v[182:185], v[112:115]
	v_mfma_f32_16x16x32_bf16 v[48:51], v[144:147], v[182:185], v[48:51]
	v_mfma_f32_16x16x32_bf16 v[104:107], v[136:139], v[190:193], v[104:107]
	v_mfma_f32_16x16x32_bf16 v[40:43], v[144:147], v[190:193], v[40:43]
	s_barrier
	s_add_i32 vcc_lo, 0, 0x14000
	s_add_i32 s45, s45, s4
	v_add_u32_e32 v220, vcc_lo, v200
	v_lshl_add_u64 v[242:243], s[42:43], 0, v[2:3]
	s_mov_b32 m0, s45
	ds_read_b128 v[194:197], v220
	ds_read_b128 v[230:233], v220 offset:1024
	ds_read_b128 v[234:237], v220 offset:2048
	ds_read_b128 v[238:241], v220 offset:3072
	global_load_lds_dwordx4 v[242:243], off
	v_lshl_add_u64 v[244:245], s[42:43], 0, v[164:165]
	s_add_i32 m0, s45, 0x2000
	s_nop 0
	global_load_lds_dwordx4 v[244:245], off
	s_barrier
	s_waitcnt lgkmcnt(0)
	s_waitcnt lgkmcnt(0)
	v_mfma_f32_16x16x32_bf16 v[124:127], v[194:197], v[148:151], v[124:127]
	v_mfma_f32_16x16x32_bf16 v[60:63], v[234:237], v[148:151], v[60:63]
	v_mfma_f32_16x16x32_bf16 v[116:119], v[194:197], v[156:159], v[116:119]
	v_mfma_f32_16x16x32_bf16 v[52:55], v[234:237], v[156:159], v[52:55]
	v_mfma_f32_16x16x32_bf16 v[108:111], v[194:197], v[178:181], v[108:111]
	v_mfma_f32_16x16x32_bf16 v[44:47], v[234:237], v[178:181], v[44:47]
	v_mfma_f32_16x16x32_bf16 v[100:103], v[194:197], v[186:189], v[100:103]
	v_mfma_f32_16x16x32_bf16 v[36:39], v[234:237], v[186:189], v[36:39]
	v_mfma_f32_16x16x32_bf16 v[124:127], v[230:233], v[152:155], v[124:127]
	v_mfma_f32_16x16x32_bf16 v[60:63], v[238:241], v[152:155], v[60:63]
	v_mfma_f32_16x16x32_bf16 v[116:119], v[230:233], v[160:163], v[116:119]
	v_mfma_f32_16x16x32_bf16 v[52:55], v[238:241], v[160:163], v[52:55]
	v_mfma_f32_16x16x32_bf16 v[108:111], v[230:233], v[182:185], v[108:111]
	v_mfma_f32_16x16x32_bf16 v[44:47], v[238:241], v[182:185], v[44:47]
	v_mfma_f32_16x16x32_bf16 v[100:103], v[230:233], v[190:193], v[100:103]
	v_mfma_f32_16x16x32_bf16 v[36:39], v[238:241], v[190:193], v[36:39]
	s_mov_b32 m0, s5
	v_lshl_add_u64 v[246:247], s[40:41], 0, v[166:167]
	s_barrier
	ds_read_b128 v[148:151], v229 offset:16384
	ds_read_b128 v[152:155], v229 offset:17408
	ds_read_b128 v[156:159], v229 offset:18432
	ds_read_b128 v[160:163], v229 offset:19456
	ds_read_b128 v[178:181], v229 offset:20480
	ds_read_b128 v[182:185], v229 offset:21504
	ds_read_b128 v[186:189], v229 offset:22528
	ds_read_b128 v[190:193], v229 offset:23552
	global_load_lds_dwordx4 v[246:247], off
	v_lshl_add_u64 v[248:249], s[40:41], 0, v[0:1]
	s_mov_b32 m0, s94
	s_nop 0
	global_load_lds_dwordx4 v[248:249], off
	s_barrier
	s_waitcnt lgkmcnt(0)
	s_waitcnt lgkmcnt(0)
	v_mfma_f32_16x16x32_bf16 v[96:99], v[132:135], v[148:151], v[96:99]
	v_mfma_f32_16x16x32_bf16 v[32:35], v[140:143], v[148:151], v[32:35]
	v_mfma_f32_16x16x32_bf16 v[88:91], v[132:135], v[156:159], v[88:91]
	v_mfma_f32_16x16x32_bf16 v[24:27], v[140:143], v[156:159], v[24:27]
	v_mfma_f32_16x16x32_bf16 v[68:71], v[132:135], v[178:181], v[68:71]
	v_mfma_f32_16x16x32_bf16 v[20:23], v[140:143], v[178:181], v[20:23]
	v_mfma_f32_16x16x32_bf16 v[84:87], v[132:135], v[186:189], v[84:87]
	v_mfma_f32_16x16x32_bf16 v[16:19], v[140:143], v[186:189], v[16:19]
	v_mfma_f32_16x16x32_bf16 v[96:99], v[136:139], v[152:155], v[96:99]
	v_mfma_f32_16x16x32_bf16 v[32:35], v[144:147], v[152:155], v[32:35]
	v_mfma_f32_16x16x32_bf16 v[88:91], v[136:139], v[160:163], v[88:91]
	v_mfma_f32_16x16x32_bf16 v[24:27], v[144:147], v[160:163], v[24:27]
	v_mfma_f32_16x16x32_bf16 v[68:71], v[136:139], v[182:185], v[68:71]
	v_mfma_f32_16x16x32_bf16 v[20:23], v[144:147], v[182:185], v[20:23]
	v_mfma_f32_16x16x32_bf16 v[84:87], v[136:139], v[190:193], v[84:87]
	v_mfma_f32_16x16x32_bf16 v[16:19], v[144:147], v[190:193], v[16:19]
	s_barrier
; #define PG8_STAGE(bufoff, gbase, voff) do { _Pragma("unroll") for (int _i = 0; _i < 2; ++_i) \
;         __builtin_amdgcn_global_load_lds((const unsigned*)((const char*)(gbase) + (voff)[_i]), (LAS unsigned*)(lds + (bufoff) + ldsw + _i * 8192), 16, 0, 0); } while (0)
; #define PG8_LDA(dst, b, h) do { _Pragma("unroll") for (int m = 0; m < 4; ++m) _Pragma("unroll") for (int k = 0; k < 2; ++k) dst[m][k] = *(const LAS bf16x8*)(lds + PG8_SA(b, h) + aoff + m * 2048 + k * 1024); } while (0)
; #define PG8_LDB(dst, b, h) do { _Pragma("unroll") for (int n = 0; n < 2; ++n) _Pragma("unroll") for (int k = 0; k < 2; ++k) dst[n][k] = *(const LAS bf16x8*)(lds + PG8_SB(b, h) + boff + n * 2048 + k * 1024); } while (0)
; #define PG8_MMA(ai, bj, At, Bt) do { __builtin_amdgcn_s_setprio(1); _Pragma("unroll") for (int m = 0; m < 4; ++m) _Pragma("unroll") for (int n = 0; n < 2; ++n) _Pragma("unroll") for (int k = 0; k < 2; ++k) \
;         acc[ai][bj][m][n] = __builtin_amdgcn_mfma_f32_16x16x32_bf16(Bt[n][k], At[m][k], acc[ai][bj][m][n], 0, 0, 0); __builtin_amdgcn_s_setprio(0); } while (0)
; #define PG8_WAIT_V(n) asm volatile("s_waitcnt vmcnt(" #n ")" ::: "memory")
; #define PG8_WAIT_L(n) asm volatile("s_waitcnt lgkmcnt(" #n ")" ::: "memory")
; #define PG8_BAR __builtin_amdgcn_s_barrier()
; #define PG8_SCHED __builtin_amdgcn_sched_barrier(0)
; __device__ __forceinline__ void gemm_phase(LAS unsigned char* lds, const GemmDesc& g) {
;     ...
;             PG8_LDA(At, 0, 1); PG8_STAGE(PG8_SA(0, 0), a2, voffA);
;             PG8_BAR; PG8_WAIT_L(0); PG8_MMA(1, 0, At, B0); PG8_BAR; PG8_SCHED;
;             PG8_STAGE(PG8_SB(0, 1), b2 + hstep, voffB);
;             PG8_WAIT_V(6); PG8_BAR; PG8_MMA(1, 1, At, B1); PG8_BAR;
;             PG8_LDB(B0, 1, 0); PG8_SCHED; PG8_LDA(At, 1, 0); PG8_STAGE(PG8_SA(0, 1), a2 + hstepA, voffA);
;             PG8_WAIT_L(8); PG8_BAR; PG8_WAIT_L(0); PG8_MMA(0, 0, At, B0); PG8_BAR; PG8_SCHED;
;             PG8_LDB(B1, 1, 1); PG8_STAGE(PG8_SB(1, 0), b3, voffB);
;             PG8_BAR; PG8_WAIT_L(0); PG8_MMA(0, 1, At, B1); PG8_BAR;
;             PG8_LDA(At, 1, 1); PG8_STAGE(PG8_SA(1, 0), a3, voffA);
	s_add_u32 s42, s42, s64
	s_addc_u32 s43, s43, s65
	s_add_i32 s45, vcc_lo, s4
	v_lshl_add_u64 v[220:221], s[42:43], 0, v[2:3]
	s_mov_b32 m0, s45
	v_lshl_add_u64 v[222:223], s[42:43], 0, v[164:165]
	global_load_lds_dwordx4 v[220:221], off
	s_add_i32 m0, s45, 0x2000
	s_nop 0
	global_load_lds_dwordx4 v[222:223], off
	s_waitcnt vmcnt(6)
	s_barrier
	v_mfma_f32_16x16x32_bf16 v[92:95], v[194:197], v[148:151], v[92:95]
	v_mfma_f32_16x16x32_bf16 v[28:31], v[234:237], v[148:151], v[28:31]
	v_mfma_f32_16x16x32_bf16 v[80:83], v[194:197], v[156:159], v[80:83]
	v_mfma_f32_16x16x32_bf16 v[12:15], v[234:237], v[156:159], v[12:15]
	v_mfma_f32_16x16x32_bf16 v[76:79], v[194:197], v[178:181], v[76:79]
	v_mfma_f32_16x16x32_bf16 v[8:11], v[234:237], v[178:181], v[8:11]
	v_mfma_f32_16x16x32_bf16 v[72:75], v[194:197], v[186:189], v[72:75]
	v_mfma_f32_16x16x32_bf16 v[4:7], v[234:237], v[186:189], v[4:7]
	v_mfma_f32_16x16x32_bf16 v[92:95], v[230:233], v[152:155], v[92:95]
	v_mfma_f32_16x16x32_bf16 v[28:31], v[238:241], v[152:155], v[28:31]
	v_mfma_f32_16x16x32_bf16 v[80:83], v[230:233], v[160:163], v[80:83]
	v_mfma_f32_16x16x32_bf16 v[12:15], v[238:241], v[160:163], v[12:15]
	v_mfma_f32_16x16x32_bf16 v[76:79], v[230:233], v[182:185], v[76:79]
	v_mfma_f32_16x16x32_bf16 v[8:11], v[238:241], v[182:185], v[8:11]
	v_mfma_f32_16x16x32_bf16 v[72:75], v[230:233], v[190:193], v[72:75]
	v_mfma_f32_16x16x32_bf16 v[4:7], v[238:241], v[190:193], v[4:7]
	s_add_i32 s42, 0, 0x18000
	v_add_u32_e32 v144, s42, v200
	s_barrier
	ds_read_b128 v[132:135], v144
	ds_read_b128 v[136:139], v144 offset:1024
	ds_read_b128 v[140:143], v144 offset:2048
	ds_read_b128 v[144:147], v144 offset:3072
	s_add_u32 s40, s40, s68
	s_addc_u32 s41, s41, s69
	s_mov_b32 m0, s70
	v_lshl_add_u64 v[194:195], s[40:41], 0, v[166:167]
	ds_read_b128 v[148:151], v229 offset:32768
	ds_read_b128 v[152:155], v229 offset:33792
	ds_read_b128 v[156:159], v229 offset:34816
	ds_read_b128 v[160:163], v229 offset:35840
	ds_read_b128 v[178:181], v229 offset:36864
	ds_read_b128 v[182:185], v229 offset:37888
	ds_read_b128 v[186:189], v229 offset:38912
	ds_read_b128 v[190:193], v229 offset:39936
	global_load_lds_dwordx4 v[194:195], off
	v_lshl_add_u64 v[194:195], s[40:41], 0, v[0:1]
	s_mov_b32 m0, s71
	s_nop 0
	global_load_lds_dwordx4 v[194:195], off
	s_waitcnt lgkmcnt(8)
	s_barrier
	s_waitcnt lgkmcnt(0)
	s_waitcnt lgkmcnt(0)
	v_mfma_f32_16x16x32_bf16 v[128:131], v[132:135], v[148:151], v[128:131]
	v_mfma_f32_16x16x32_bf16 v[64:67], v[140:143], v[148:151], v[64:67]
	v_mfma_f32_16x16x32_bf16 v[120:123], v[132:135], v[156:159], v[120:123]
	v_mfma_f32_16x16x32_bf16 v[56:59], v[140:143], v[156:159], v[56:59]
	v_mfma_f32_16x16x32_bf16 v[112:115], v[132:135], v[178:181], v[112:115]
	v_mfma_f32_16x16x32_bf16 v[48:51], v[140:143], v[178:181], v[48:51]
	v_mfma_f32_16x16x32_bf16 v[104:107], v[132:135], v[186:189], v[104:107]
	v_mfma_f32_16x16x32_bf16 v[40:43], v[140:143], v[186:189], v[40:43]
	v_mfma_f32_16x16x32_bf16 v[128:131], v[136:139], v[152:155], v[128:131]
	v_mfma_f32_16x16x32_bf16 v[64:67], v[144:147], v[152:155], v[64:67]
	v_mfma_f32_16x16x32_bf16 v[120:123], v[136:139], v[160:163], v[120:123]
	v_mfma_f32_16x16x32_bf16 v[56:59], v[144:147], v[160:163], v[56:59]
	v_mfma_f32_16x16x32_bf16 v[112:115], v[136:139], v[182:185], v[112:115]
	v_mfma_f32_16x16x32_bf16 v[48:51], v[144:147], v[182:185], v[48:51]
	v_mfma_f32_16x16x32_bf16 v[104:107], v[136:139], v[190:193], v[104:107]
	v_mfma_f32_16x16x32_bf16 v[40:43], v[144:147], v[190:193], v[40:43]
	s_barrier
	s_add_i32 s40, 0, 0x1c000
	s_add_i32 s41, s42, s4
	v_add_u32_e32 v238, s40, v200
	v_lshl_add_u64 v[242:243], v[242:243], 0, s[20:21]
	s_mov_b32 m0, s41
	ds_read_b128 v[194:197], v238
	ds_read_b128 v[230:233], v238 offset:1024
	ds_read_b128 v[234:237], v238 offset:2048
	ds_read_b128 v[238:241], v238 offset:3072
	global_load_lds_dwordx4 v[242:243], off
	v_lshl_add_u64 v[242:243], v[244:245], 0, s[20:21]
	s_add_i32 m0, s41, 0x2000
	s_nop 0
	global_load_lds_dwordx4 v[242:243], off
	s_barrier
; #define PG8_STAGE(bufoff, gbase, voff) do { _Pragma("unroll") for (int _i = 0; _i < 2; ++_i) \
;         __builtin_amdgcn_global_load_lds((const unsigned*)((const char*)(gbase) + (voff)[_i]), (LAS unsigned*)(lds + (bufoff) + ldsw + _i * 8192), 16, 0, 0); } while (0)
; #define PG8_LDA(dst, b, h) do { _Pragma("unroll") for (int m = 0; m < 4; ++m) _Pragma("unroll") for (int k = 0; k < 2; ++k) dst[m][k] = *(const LAS bf16x8*)(lds + PG8_SA(b, h) + aoff + m * 2048 + k * 1024); } while (0)
; #define PG8_LDB(dst, b, h) do { _Pragma("unroll") for (int n = 0; n < 2; ++n) _Pragma("unroll") for (int k = 0; k < 2; ++k) dst[n][k] = *(const LAS bf16x8*)(lds + PG8_SB(b, h) + boff + n * 2048 + k * 1024); } while (0)
; #define PG8_MMA(ai, bj, At, Bt) do { __builtin_amdgcn_s_setprio(1); _Pragma("unroll") for (int m = 0; m < 4; ++m) _Pragma("unroll") for (int n = 0; n < 2; ++n) _Pragma("unroll") for (int k = 0; k < 2; ++k) \
;         acc[ai][bj][m][n] = __builtin_amdgcn_mfma_f32_16x16x32_bf16(Bt[n][k], At[m][k], acc[ai][bj][m][n], 0, 0, 0); __builtin_amdgcn_s_setprio(0); } while (0)
; #define PG8_WAIT_V(n) asm volatile("s_waitcnt vmcnt(" #n ")" ::: "memory")
; #define PG8_WAIT_L(n) asm volatile("s_waitcnt lgkmcnt(" #n ")" ::: "memory")
; #define PG8_BAR __builtin_amdgcn_s_barrier()
; #define PG8_SCHED __builtin_amdgcn_sched_barrier(0)
; __device__ __forceinline__ void gemm_phase(LAS unsigned char* lds, const GemmDesc& g) {
;     ...
;             PG8_WAIT_L(8); PG8_BAR; PG8_WAIT_L(0); PG8_MMA(0, 0, At, B0); PG8_BAR; PG8_SCHED;
;             PG8_LDB(B1, 1, 1); PG8_STAGE(PG8_SB(1, 0), b3, voffB);
;             PG8_BAR; PG8_WAIT_L(0); PG8_MMA(0, 1, At, B1); PG8_BAR;
;             PG8_LDA(At, 1, 1); PG8_STAGE(PG8_SA(1, 0), a3, voffA);
;             PG8_BAR; PG8_WAIT_L(0); PG8_MMA(1, 0, At, B0); PG8_BAR; PG8_SCHED;
;             PG8_STAGE(PG8_SB(1, 1), b3 + hstep, voffB);
;             PG8_WAIT_V(6); PG8_BAR; PG8_MMA(1, 1, At, B1); PG8_BAR;
	s_waitcnt lgkmcnt(0)
	s_waitcnt lgkmcnt(0)
	v_mfma_f32_16x16x32_bf16 v[124:127], v[194:197], v[148:151], v[124:127]
	v_mfma_f32_16x16x32_bf16 v[60:63], v[234:237], v[148:151], v[60:63]
	v_mfma_f32_16x16x32_bf16 v[116:119], v[194:197], v[156:159], v[116:119]
	v_mfma_f32_16x16x32_bf16 v[52:55], v[234:237], v[156:159], v[52:55]
	v_mfma_f32_16x16x32_bf16 v[108:111], v[194:197], v[178:181], v[108:111]
	v_mfma_f32_16x16x32_bf16 v[44:47], v[234:237], v[178:181], v[44:47]
	v_mfma_f32_16x16x32_bf16 v[100:103], v[194:197], v[186:189], v[100:103]
	v_mfma_f32_16x16x32_bf16 v[36:39], v[234:237], v[186:189], v[36:39]
	v_mfma_f32_16x16x32_bf16 v[124:127], v[230:233], v[152:155], v[124:127]
	v_mfma_f32_16x16x32_bf16 v[60:63], v[238:241], v[152:155], v[60:63]
	v_mfma_f32_16x16x32_bf16 v[116:119], v[230:233], v[160:163], v[116:119]
	v_mfma_f32_16x16x32_bf16 v[52:55], v[238:241], v[160:163], v[52:55]
	v_mfma_f32_16x16x32_bf16 v[108:111], v[230:233], v[182:185], v[108:111]
	v_mfma_f32_16x16x32_bf16 v[44:47], v[238:241], v[182:185], v[44:47]
	v_mfma_f32_16x16x32_bf16 v[100:103], v[230:233], v[190:193], v[100:103]
	v_mfma_f32_16x16x32_bf16 v[36:39], v[238:241], v[190:193], v[36:39]
	s_mov_b32 m0, s49
	v_lshl_add_u64 v[242:243], v[246:247], 0, s[20:21]
	s_barrier
	ds_read_b128 v[148:151], v229 offset:49152
	ds_read_b128 v[152:155], v229 offset:50176
	ds_read_b128 v[156:159], v229 offset:51200
	ds_read_b128 v[160:163], v229 offset:52224
	ds_read_b128 v[178:181], v229 offset:53248
	ds_read_b128 v[182:185], v229 offset:54272
	ds_read_b128 v[186:189], v229 offset:55296
	ds_read_b128 v[190:193], v229 offset:56320
	global_load_lds_dwordx4 v[242:243], off
	v_lshl_add_u64 v[242:243], v[248:249], 0, s[20:21]
	s_mov_b32 m0, s62
	s_nop 0
	global_load_lds_dwordx4 v[242:243], off
	s_barrier
	s_waitcnt lgkmcnt(0)
	s_waitcnt lgkmcnt(0)
	v_mfma_f32_16x16x32_bf16 v[96:99], v[132:135], v[148:151], v[96:99]
	v_mfma_f32_16x16x32_bf16 v[32:35], v[140:143], v[148:151], v[32:35]
	v_mfma_f32_16x16x32_bf16 v[88:91], v[132:135], v[156:159], v[88:91]
	v_mfma_f32_16x16x32_bf16 v[24:27], v[140:143], v[156:159], v[24:27]
	v_mfma_f32_16x16x32_bf16 v[68:71], v[132:135], v[178:181], v[68:71]
	v_mfma_f32_16x16x32_bf16 v[20:23], v[140:143], v[178:181], v[20:23]
	v_mfma_f32_16x16x32_bf16 v[84:87], v[132:135], v[186:189], v[84:87]
	v_mfma_f32_16x16x32_bf16 v[16:19], v[140:143], v[186:189], v[16:19]
	v_mfma_f32_16x16x32_bf16 v[96:99], v[136:139], v[152:155], v[96:99]
	v_mfma_f32_16x16x32_bf16 v[32:35], v[144:147], v[152:155], v[32:35]
	v_mfma_f32_16x16x32_bf16 v[88:91], v[136:139], v[160:163], v[88:91]
	v_mfma_f32_16x16x32_bf16 v[24:27], v[144:147], v[160:163], v[24:27]
	v_mfma_f32_16x16x32_bf16 v[68:71], v[136:139], v[182:185], v[68:71]
	v_mfma_f32_16x16x32_bf16 v[20:23], v[144:147], v[182:185], v[20:23]
	v_mfma_f32_16x16x32_bf16 v[84:87], v[136:139], v[190:193], v[84:87]
	v_mfma_f32_16x16x32_bf16 v[16:19], v[144:147], v[190:193], v[16:19]
	s_barrier
	s_add_i32 s40, s40, s4
	v_lshl_add_u64 v[132:133], v[220:221], 0, s[20:21]
	s_mov_b32 m0, s40
	s_nop 0
	global_load_lds_dwordx4 v[132:133], off
	v_lshl_add_u64 v[132:133], v[222:223], 0, s[20:21]
	s_add_i32 m0, s40, 0x2000
	s_nop 0
	global_load_lds_dwordx4 v[132:133], off
	s_waitcnt vmcnt(6)
	s_barrier
	v_mfma_f32_16x16x32_bf16 v[92:95], v[194:197], v[148:151], v[92:95]
	v_mfma_f32_16x16x32_bf16 v[28:31], v[234:237], v[148:151], v[28:31]
	v_mfma_f32_16x16x32_bf16 v[80:83], v[194:197], v[156:159], v[80:83]
	v_mfma_f32_16x16x32_bf16 v[12:15], v[234:237], v[156:159], v[12:15]
	v_mfma_f32_16x16x32_bf16 v[76:79], v[194:197], v[178:181], v[76:79]
	v_mfma_f32_16x16x32_bf16 v[8:11], v[234:237], v[178:181], v[8:11]
	v_mfma_f32_16x16x32_bf16 v[72:75], v[194:197], v[186:189], v[72:75]
	v_mfma_f32_16x16x32_bf16 v[4:7], v[234:237], v[186:189], v[4:7]
	v_mfma_f32_16x16x32_bf16 v[92:95], v[230:233], v[152:155], v[92:95]
	v_mfma_f32_16x16x32_bf16 v[28:31], v[238:241], v[152:155], v[28:31]
	v_mfma_f32_16x16x32_bf16 v[80:83], v[230:233], v[160:163], v[80:83]
	v_mfma_f32_16x16x32_bf16 v[12:15], v[238:241], v[160:163], v[12:15]
	v_mfma_f32_16x16x32_bf16 v[76:79], v[230:233], v[182:185], v[76:79]
	v_mfma_f32_16x16x32_bf16 v[8:11], v[238:241], v[182:185], v[8:11]
	v_mfma_f32_16x16x32_bf16 v[72:75], v[230:233], v[190:193], v[72:75]
	v_mfma_f32_16x16x32_bf16 v[4:7], v[238:241], v[190:193], v[4:7]
	s_add_u32 s0, s0, 0x100
	s_addc_u32 s1, s1, 0
	s_add_u32 s13, s13, 0x100
	s_addc_u32 s18, s18, 0
	s_cmp_ge_u32 s44, s48
	s_mov_b32 s40, s44
	s_barrier
	s_cbranch_scc0 .LBB0_208
	s_branch .LBB0_214

; #define LAS __attribute__((address_space(3)))
; __global__ void __launch_bounds__(512, 2) fwd_megakernel(Params p) {
;     ...
;             unsigned* ctr = (unsigned*)(ws + OFF_CTR) + rep;
;             if (EN(8)) {
;                 if (threadIdx.x == 0) *(LAS int*)(lds + LDS_SLOT) = (int)atomicAdd(ctr, 1u);
.LBB0_409:
	v_readlane_b32 s0, v254, 40
	v_readlane_b32 s1, v254, 41
	s_andn2_b64 vcc, exec, s[0:1]
	s_cbranch_vccnz .LBB0_23
	v_readlane_b32 s0, v254, 44
	v_readlane_b32 s1, v254, 45
	s_lshl_b64 s[0:1], s[0:1], 2
	v_readlane_b32 s2, v251, 57
	v_readlane_b32 s3, v251, 58
	s_add_u32 s2, s2, s0
	s_addc_u32 s3, s3, s1
	s_and_saveexec_b64 s[0:1], s[62:63]
	s_cbranch_execz .LBB0_414
	s_mov_b64 s[6:7], exec
	v_mbcnt_lo_u32_b32 v0, s6, 0
	v_mbcnt_hi_u32_b32 v0, s7, v0
	v_cmp_eq_u32_e32 vcc, 0, v0
	s_and_saveexec_b64 s[4:5], vcc
	s_cbranch_execz .LBB0_413
	v_mov_b32_e32 v1, 2
	global_atomic_add v1, v3, v1, s[2:3] sc0

; #define LAS __attribute__((address_space(3)))
; __device__ __forceinline__ int opaque_tid() { int t = (int)threadIdx.x; asm volatile("" : "+v"(t)); return t; }
; __device__ __forceinline__ void dil_preload(const Params& p, int item, int tid, u32x4 (&pk)[8], u32x4 (&pv)[8]) {
;     const int pat = item >> 10, rem = item & 1023, b = rem >> 8, head = (rem >> 5) & 7, sb = rem & 31;
;     const int dsh = pat * 2, nbsh = 5 - dsh;
;     const int r = sb >> nbsh, blk = sb & ((1 << nbsh) - 1);
;     const bf16_t* hb = (const bf16_t*)(p.ws + OFF_H) + (size_t)(b * SEQ) * HC;
;     const int piece = tid & 15;
; #pragma unroll
;     for (int it = 0; it < 8; ++it) {
;         const int row = (tid >> 4) + 32 * it, lj = (blk - 1) * 128 + row;
;         u32x4 kv = {0u, 0u, 0u, 0u}, vv = kv;
;         if (lj >= 0) { const int pos = r + (lj << dsh); const bf16_t* rp = hb + (size_t)pos * HC + head * 128 + piece * 8; kv = *(const u32x4*)(rp + 4096); vv = *(const u32x4*)(rp + 5120); }
;         pk[it] = kv; pv[it] = vv;
;     }
; __global__ void __launch_bounds__(512, 2) fwd_megakernel(Params p) {
;     ...
;                 if (threadIdx.x == 0) *(LAS int*)(lds + LDS_SLOT) = (int)atomicAdd(ctr, 1u);
;                 __syncthreads();
;                 int item = *(LAS int*)(lds + LDS_SLOT);
;                 __syncthreads();
;                 if (item < 3072) {
;                     u32x4 pk[8], pv[8];
;                     dil_preload(p, item, opaque_tid(), pk, pv);
.LBB0_414:
	s_or_b64 exec, exec, s[0:1]
	v_mov_b32_e32 v0, s38
	s_waitcnt vmcnt(0) lgkmcnt(0)
	s_barrier
	ds_read_b32 v0, v0
	s_movk_i32 s0, 0xbff
	s_waitcnt lgkmcnt(0)
	s_barrier
	v_cmp_lt_i32_e32 vcc, s0, v0
	v_readfirstlane_b32 s8, v0
	v_add_u32_e32 v86, 1, v0
	s_cbranch_vccnz .LBB0_459
	s_ashr_i32 s1, s8, 9
	s_and_b32 s4, s1, -2
	s_and_b32 s0, s8, 31
	s_sub_i32 s1, 5, s4
	s_lshr_b32 s5, s0, s1
	s_lshl_b32 s1, -1, s1
	s_andn2_b32 s0, s0, s1
	s_lshl_b32 s1, s8, 4
	s_and_b32 s1, s1, 0x3000
	v_mov_b32_e32 v0, v212
	s_mulk_i32 s1, 0x3000
	s_add_u32 s1, s26, s1
	v_ashrrev_i32_e32 v1, 4, v0
	s_addc_u32 s6, s27, 0
	v_lshl_add_u32 v68, s0, 7, v1
	s_lshl_b32 s0, s8, 3
	s_and_b32 s0, s0, 0x700
	s_add_u32 s0, s1, s0
	v_lshlrev_b32_e32 v0, 4, v0
	s_addc_u32 s1, s6, 0
	v_and_b32_e32 v2, 0xf0, v0
	v_lshl_add_u64 v[0:1], s[0:1], 0, v[2:3]
	v_cmp_lt_i32_e32 vcc, s33, v68
	v_mov_b32_e32 v4, 0
	v_mov_b32_e32 v8, 0
	v_mov_b32_e32 v9, 0
	v_mov_b32_e32 v10, 0
	v_mov_b32_e32 v11, 0
	v_mov_b32_e32 v12, 0
	v_mov_b32_e32 v13, 0
	v_mov_b32_e32 v14, 0
	v_mov_b32_e32 v15, 0
	s_and_saveexec_b64 s[0:1], vcc
	s_cbranch_execz .LBB0_417
	v_add_u32_e32 v2, 0xffffff80, v68
	v_lshlrev_b32_e32 v2, s4, v2
	v_add_u32_e32 v2, s5, v2
	v_mad_i64_i32 v[6:7], s[6:7], v2, s48, v[0:1]
	v_add_co_u32_e32 v6, vcc, 0x2000, v6
	s_nop 1
	v_addc_co_u32_e32 v7, vcc, 0, v7, vcc
	global_load_dwordx4 v[12:15], v[6:7], off
	global_load_dwordx4 v[8:11], v[6:7], off offset:2048

; #define LAS __attribute__((address_space(3)))
; #define LDS_BARRIER() do { asm volatile("s_waitcnt lgkmcnt(0)" ::: "memory"); __builtin_amdgcn_s_barrier(); asm volatile("" ::: "memory"); } while (0)
; __device__ __forceinline__ void dilated_item(const Params& p, int item, int next, u32x4 (&pk)[8], u32x4 (&pv)[8], LAS unsigned char* lds) {
;     ...
;     { const int piece = tid & 15;
; #pragma unroll
;       for (int it = 0; it < 8; ++it) { const int row = (tid >> 4) + 32 * it;
;           *(LAS u32x4*)(lds + row * KV_STRIDE + piece * 16) = pk[it]; *(LAS u32x4*)(lds + KV_BUF + row * KV_STRIDE + piece * 16) = pv[it]; } }
; __global__ void __launch_bounds__(512, 2) fwd_megakernel(Params p) {
;     ...
;                     while (item < 3072) {
;                         if (threadIdx.x == 0) *(LAS int*)(lds + LDS_SLOT) = (int)atomicAdd(ctr, 1u);
;                         LDS_BARRIER();
;                         const int next = *(LAS int*)(lds + LDS_SLOT);
.LBB0_431:
	s_or_b64 exec, exec, s[0:1]
	s_waitcnt vmcnt(0)
	s_branch .LBB0_433
.LBB0_432:
	s_or_b64 exec, exec, s[0:1]
	s_and_saveexec_b64 s[0:1], s[62:63]
	s_cbranch_execz .Ldil_noslot
	s_waitcnt vmcnt(8)
	v_mov_b32_e32 v161, s38
	ds_write_b32 v161, v160
.Ldil_noslot:
	s_or_b64 exec, exec, s[0:1]
	s_waitcnt lgkmcnt(0)
	s_barrier
	v_mov_b32_e32 v161, s38
	ds_read_b32 v86, v161
	s_waitcnt lgkmcnt(0)
	v_readlane_b32 s24, v254, 17
	s_andn2_b64 vcc, exec, s[36:37]
	s_mov_b32 s8, s10
	v_readlane_b32 s25, v254, 18
	s_cbranch_vccz .LBB0_459
.LBB0_433:
	s_ashr_i32 s4, s8, 10
	s_lshl_b32 s10, s4, 1
	s_sub_i32 s0, 5, s10
	s_lshl_b32 s5, s8, 4
	s_lshl_b32 s1, -1, s0
	s_and_b32 s5, s5, 0x3000
	s_and_b32 s6, s8, 31
	v_mov_b32_e32 v84, v212
	s_bfe_u32 s9, s8, 0x30005
	s_add_i32 s11, 0, 0x11000
	s_lshr_b32 s12, s6, s0
	s_andn2_b32 s6, s6, s1
	s_mul_i32 s0, s5, 0x3000
	s_add_u32 s0, s92, s0
	v_readfirstlane_b32 s7, v84
	s_addc_u32 s1, s93, 0
	s_ashr_i32 s7, s7, 2
	s_lshl_b32 s15, s6, 7
	s_and_b32 s13, s7, -16
	v_and_b32_e32 v118, 15, v84
	s_add_i32 s7, s13, s15
	v_or_b32_e32 v0, s7, v118
	v_lshlrev_b32_e32 v0, s10, v0
	v_add_u32_e32 v117, s12, v0
	v_mov_b64_e32 v[0:1], s[0:1]
	v_bfe_u32 v116, v84, 4, 2
	v_mad_i64_i32 v[0:1], s[0:1], v117, s48, v[0:1]
	s_lshl_b32 s18, s9, 8
	v_lshl_add_u64 v[0:1], v[0:1], 0, s[18:19]
	v_lshlrev_b32_e32 v2, 4, v116
	v_lshl_add_u64 v[0:1], v[0:1], 0, v[2:3]
	s_mov_b64 s[0:1], 0xd101800
	v_lshl_add_u64 v[68:69], v[0:1], 0, s[0:1]
	v_add_co_u32_e32 v0, vcc, 0xd101000, v0
	v_ashrrev_i32_e32 v85, 4, v84
	s_nop 0
	v_addc_co_u32_e32 v1, vcc, 0, v1, vcc
	global_load_dwordx4 v[76:79], v[68:69], off offset:64
	global_load_dwordx4 v[72:75], v[68:69], off offset:128
	global_load_dwordx4 v[80:83], v[0:1], off offset:2048
	s_nop 0
	global_load_dwordx4 v[68:71], v[68:69], off offset:192
	v_lshlrev_b32_e32 v0, 4, v84
	s_movk_i32 s7, 0xbff
	v_and_b32_e32 v0, 0xf0, v0
	v_mul_lo_u32 v1, v85, s99
	s_waitcnt lgkmcnt(0)
	v_cmp_lt_i32_e64 s[36:37], s7, v86
	s_movk_i32 s7, 0xc00
	v_add3_u32 v2, 0, v0, v1
	v_add3_u32 v1, s11, v0, v1
	v_cmp_gt_i32_e32 vcc, s7, v86
	v_readfirstlane_b32 s10, v86
	s_waitcnt vmcnt(13)
	ds_write_b128 v2, v[12:15]
	ds_write_b128 v1, v[8:11]
	ds_write_b128 v2, v[16:19] offset:8704
	ds_write_b128 v1, v[4:7] offset:8704
	ds_write_b128 v2, v[28:31] offset:17408
	ds_write_b128 v1, v[24:27] offset:17408
	ds_write_b128 v2, v[32:35] offset:26112
	ds_write_b128 v1, v[20:23] offset:26112
	ds_write_b128 v2, v[44:47] offset:34816
	ds_write_b128 v1, v[40:43] offset:34816
	ds_write_b128 v2, v[48:51] offset:43520
	ds_write_b128 v1, v[36:39] offset:43520
	ds_write_b128 v2, v[60:63] offset:52224
	ds_write_b128 v1, v[56:59] offset:52224
	ds_write_b128 v2, v[64:67] offset:60928
	ds_write_b128 v1, v[52:55] offset:60928
	s_mov_b64 s[0:1], -1
	v_lshlrev_b32_e32 v2, 3, v84
	s_cbranch_vccnz .LBB0_439
	v_lshlrev_b32_e32 v1, 3, v84
	s_mov_b64 s[0:1], 0

; #define LAS __attribute__((address_space(3)))
; __device__ __forceinline__ f32x4 mfma16(bf16x8 a, bf16x8 b, f32x4 c) { return __builtin_amdgcn_mfma_f32_16x16x32_bf16(a, b, c, 0, 0, 0); }
; #define LDS_BARRIER() do { asm volatile("s_waitcnt lgkmcnt(0)" ::: "memory"); __builtin_amdgcn_s_barrier(); asm volatile("" ::: "memory"); } while (0)
; __device__ __forceinline__ void dilated_item(const Params& p, int item, int next, u32x4 (&pk)[8], u32x4 (&pv)[8], LAS unsigned char* lds) {
;     ...
;     const int qpos = r + ((blk * 128 + 16 * w + idx) << dsh);
;     bf16x8 qf[4];
;     { const bf16_t* qp = hb + (size_t)qpos * HC + 3072 + head * 128 + 8 * g;
; #pragma unroll
;       for (int ks = 0; ks < 4; ++ks) qf[ks] = *(const bf16x8*)(qp + 32 * ks); }
;     if (next < 3072) dil_preload(p, next, tid, pk, pv);
;     LDS_BARRIER();
;     f32x4 sc[9];
; #pragma unroll
;     for (int tt = 0; tt < 9; ++tt) {
;         sc[tt] = (f32x4){0.f, 0.f, 0.f, 0.f};
; #pragma unroll
;         for (int ks = 0; ks < 4; ++ks) sc[tt] = mfma16(frag_row(lds, KV_STRIDE, 16 * (w + tt), 32 * ks, idx, g), qf[ks], sc[tt]);
; __global__ void __launch_bounds__(512, 2) fwd_megakernel(Params p) {
;     ...
;                         if (threadIdx.x == 0) *(LAS int*)(lds + LDS_SLOT) = (int)atomicAdd(ctr, 1u);
.LBB0_457:
	s_and_saveexec_b64 s[0:1], s[62:63]
	s_cbranch_execz .Ldil_noatom
	global_atomic_add v160, v3, v214, s[2:3] sc0
.Ldil_noatom:
	s_or_b64 exec, exec, s[0:1]
	v_lshl_add_u32 v0, v116, 4, 0
	v_or_b32_e32 v2, s13, v118
	s_waitcnt lgkmcnt(0)
	s_barrier
	v_mad_u64_u32 v[92:93], s[0:1], v2, s99, v[0:1]
	ds_read_b128 v[84:87], v92
	ds_read_b128 v[88:91], v92 offset:64
	s_add_i32 s25, s13, 16
	v_or_b32_e32 v2, s25, v118
	s_ashr_i32 vcc_lo, s10, 10
	s_lshl_b32 vcc_lo, vcc_lo, 1
	s_sub_i32 vcc_lo, 5, vcc_lo
	s_lshl_b32 vcc_hi, -1, vcc_lo
	s_andn2_b32 vcc_lo, s10, vcc_hi
	s_cmp_eq_u32 vcc_lo, 0
	s_cbranch_scc1 .Ldil_q8a
	s_waitcnt vmcnt(17) lgkmcnt(1)
	s_branch .Ldil_qa
.Ldil_q8a:
	s_waitcnt vmcnt(9) lgkmcnt(1)
.Ldil_qa:
	v_mfma_f32_16x16x32_bf16 v[84:87], v[84:87], v[80:83], 0
	s_add_i32 s24, s13, 32
	s_add_i32 s23, s13, 48
	s_add_i32 s22, s13, 64
	s_waitcnt lgkmcnt(0)
	v_mfma_f32_16x16x32_bf16 v[84:87], v[88:91], v[76:79], v[84:87]
	ds_read_b128 v[88:91], v92 offset:128
	s_add_i32 s18, s13, 0x50
	s_add_i32 s17, s13, 0x60
	s_waitcnt lgkmcnt(0)
	v_mfma_f32_16x16x32_bf16 v[84:87], v[88:91], v[72:75], v[84:87]
	ds_read_b128 v[88:91], v92 offset:192
	v_mad_u64_u32 v[92:93], s[0:1], v2, s99, v[0:1]
	s_ashr_i32 vcc_lo, s10, 10
	s_lshl_b32 vcc_lo, vcc_lo, 1
	s_sub_i32 vcc_lo, 5, vcc_lo
	s_lshl_b32 vcc_hi, -1, vcc_lo
	s_andn2_b32 vcc_lo, s10, vcc_hi
	s_cmp_eq_u32 vcc_lo, 0
	s_cbranch_scc1 .Ldil_q8b
	s_waitcnt vmcnt(16) lgkmcnt(0)
	s_branch .Ldil_qb
.Ldil_q8b:
	s_waitcnt vmcnt(8) lgkmcnt(0)
.Ldil_qb:
	v_mfma_f32_16x16x32_bf16 v[108:111], v[88:91], v[68:71], v[84:87]
	s_nop 3
	ds_read_b128 v[84:87], v92
	ds_read_b128 v[88:91], v92 offset:64
	v_or_b32_e32 v2, s24, v118
	s_waitcnt lgkmcnt(1)
	v_mfma_f32_16x16x32_bf16 v[84:87], v[84:87], v[80:83], 0
	s_add_i32 s16, s13, 0x70
	s_add_i32 s15, s13, 0x80
	s_lshl_b32 s12, s9, 7
	s_waitcnt lgkmcnt(0)
	v_mfma_f32_16x16x32_bf16 v[84:87], v[88:91], v[76:79], v[84:87]
	ds_read_b128 v[88:91], v92 offset:128
	s_cmp_lg_u32 s6, 0
	s_cselect_b64 s[6:7], -1, 0
	s_waitcnt lgkmcnt(0)
	v_mfma_f32_16x16x32_bf16 v[84:87], v[88:91], v[72:75], v[84:87]
	ds_read_b128 v[88:91], v92 offset:192
	v_mad_u64_u32 v[92:93], s[0:1], v2, s99, v[0:1]
	s_waitcnt lgkmcnt(0)
	v_mfma_f32_16x16x32_bf16 v[112:115], v[88:91], v[68:71], v[84:87]
	s_nop 3
	ds_read_b128 v[84:87], v92
	ds_read_b128 v[88:91], v92 offset:64
	v_or_b32_e32 v2, s23, v118
	s_waitcnt lgkmcnt(1)
	v_mfma_f32_16x16x32_bf16 v[84:87], v[84:87], v[80:83], 0
	s_waitcnt lgkmcnt(0)
	v_mfma_f32_16x16x32_bf16 v[84:87], v[88:91], v[76:79], v[84:87]
	ds_read_b128 v[88:91], v92 offset:128
	s_waitcnt lgkmcnt(0)
	v_mfma_f32_16x16x32_bf16 v[84:87], v[88:91], v[72:75], v[84:87]
	ds_read_b128 v[88:91], v92 offset:192
	v_mad_u64_u32 v[92:93], s[0:1], v2, s99, v[0:1]
	s_waitcnt lgkmcnt(0)
	v_mfma_f32_16x16x32_bf16 v[104:107], v[88:91], v[68:71], v[84:87]
	s_nop 3
	ds_read_b128 v[84:87], v92
	ds_read_b128 v[88:91], v92 offset:64
	v_or_b32_e32 v2, s22, v118
	s_waitcnt lgkmcnt(1)
	v_mfma_f32_16x16x32_bf16 v[84:87], v[84:87], v[80:83], 0
	s_waitcnt lgkmcnt(0)
	v_mfma_f32_16x16x32_bf16 v[84:87], v[88:91], v[76:79], v[84:87]
	ds_read_b128 v[88:91], v92 offset:128
	s_waitcnt lgkmcnt(0)
	v_mfma_f32_16x16x32_bf16 v[84:87], v[88:91], v[72:75], v[84:87]
	ds_read_b128 v[88:91], v92 offset:192
	v_mad_u64_u32 v[92:93], s[0:1], v2, s99, v[0:1]
	s_waitcnt lgkmcnt(0)
	v_mfma_f32_16x16x32_bf16 v[100:103], v[88:91], v[68:71], v[84:87]
	s_nop 3
	ds_read_b128 v[84:87], v92
	ds_read_b128 v[88:91], v92 offset:64
	v_or_b32_e32 v2, s18, v118
	s_waitcnt lgkmcnt(1)
	v_mfma_f32_16x16x32_bf16 v[84:87], v[84:87], v[80:83], 0
	s_waitcnt lgkmcnt(0)
	v_mfma_f32_16x16x32_bf16 v[84:87], v[88:91], v[76:79], v[84:87]
	ds_read_b128 v[88:91], v92 offset:128
	s_waitcnt lgkmcnt(0)
	v_mfma_f32_16x16x32_bf16 v[84:87], v[88:91], v[72:75], v[84:87]
	ds_read_b128 v[88:91], v92 offset:192
	v_mad_u64_u32 v[92:93], s[0:1], v2, s99, v[0:1]
	s_waitcnt lgkmcnt(0)
	v_mfma_f32_16x16x32_bf16 v[96:99], v[88:91], v[68:71], v[84:87]
	s_nop 3
	ds_read_b128 v[84:87], v92
	ds_read_b128 v[88:91], v92 offset:64
	v_or_b32_e32 v2, s17, v118
	s_waitcnt lgkmcnt(1)
	v_mfma_f32_16x16x32_bf16 v[84:87], v[84:87], v[80:83], 0
	v_mad_u64_u32 v[120:121], s[0:1], v2, s99, v[0:1]
	v_or_b32_e32 v2, s16, v118
	s_waitcnt lgkmcnt(0)
	v_mfma_f32_16x16x32_bf16 v[84:87], v[88:91], v[76:79], v[84:87]
	ds_read_b128 v[88:91], v92 offset:128
	v_mad_u64_u32 v[124:125], s[0:1], v2, s99, v[0:1]
	s_waitcnt lgkmcnt(0)
	v_mfma_f32_16x16x32_bf16 v[84:87], v[88:91], v[72:75], v[84:87]
	ds_read_b128 v[88:91], v92 offset:192
	v_or_b32_e32 v2, s15, v118
	s_waitcnt lgkmcnt(0)
	v_mfma_f32_16x16x32_bf16 v[92:95], v[88:91], v[68:71], v[84:87]
	s_nop 3
	ds_read_b128 v[84:87], v120
	ds_read_b128 v[88:91], v120 offset:64
	s_waitcnt lgkmcnt(1)
	v_mfma_f32_16x16x32_bf16 v[84:87], v[84:87], v[80:83], 0
	s_waitcnt lgkmcnt(0)
	v_mfma_f32_16x16x32_bf16 v[84:87], v[88:91], v[76:79], v[84:87]
	ds_read_b128 v[88:91], v120 offset:128
	s_waitcnt lgkmcnt(0)
	v_mfma_f32_16x16x32_bf16 v[84:87], v[88:91], v[72:75], v[84:87]
	ds_read_b128 v[88:91], v120 offset:192
	ds_read_b128 v[120:123], v124 offset:64
	s_waitcnt lgkmcnt(1)
	v_mfma_f32_16x16x32_bf16 v[88:91], v[88:91], v[68:71], v[84:87]
	s_nop 3
	ds_read_b128 v[84:87], v124
	s_nop 2
	v_mul_f32_e32 v88, 0x3fb8aa3b, v88
	s_waitcnt lgkmcnt(0)
	v_mfma_f32_16x16x32_bf16 v[84:87], v[84:87], v[80:83], 0
	v_mul_f32_e32 v89, 0x3fb8aa3b, v89
	v_mul_f32_e32 v90, 0x3fb8aa3b, v90
	v_mul_f32_e32 v91, 0x3fb8aa3b, v91
	v_mfma_f32_16x16x32_bf16 v[84:87], v[120:123], v[76:79], v[84:87]
	ds_read_b128 v[120:123], v124 offset:128
	s_waitcnt lgkmcnt(0)
; __device__ __forceinline__ f32x4 mfma16(bf16x8 a, bf16x8 b, f32x4 c) { return __builtin_amdgcn_mfma_f32_16x16x32_bf16(a, b, c, 0, 0, 0); }
; __device__ __forceinline__ void dilated_item(const Params& p, int item, int next, u32x4 (&pk)[8], u32x4 (&pv)[8], LAS unsigned char* lds) {
;     ...
;     for (int tt = 0; tt < 9; ++tt) {
;         sc[tt] = (f32x4){0.f, 0.f, 0.f, 0.f};
; #pragma unroll
;         for (int ks = 0; ks < 4; ++ks) sc[tt] = mfma16(frag_row(lds, KV_STRIDE, 16 * (w + tt), 32 * ks, idx, g), qf[ks], sc[tt]);
;     }
;     const int qi = 128 + 16 * w + idx;
;     float mx = -1e30f;
; #pragma unroll
;     for (int tt = 0; tt < 9; ++tt)
; #pragma unroll
;         for (int rr = 0; rr < 4; ++rr) {
;             const int kj = 16 * (w + tt) + 4 * g + rr, diff = qi - kj;
;             const bool valid = (diff >= 0) && (diff <= 128) && (blk > 0 || kj >= 128);
;             const float s = valid ? sc[tt][rr] * LOG2E : -1e30f;
;             sc[tt][rr] = s; mx = fmaxf(mx, s);
;         }
	v_mfma_f32_16x16x32_bf16 v[84:87], v[120:123], v[72:75], v[84:87]
	ds_read_b128 v[120:123], v124 offset:192
	v_mad_u64_u32 v[124:125], s[0:1], v2, s99, v[0:1]
	s_waitcnt lgkmcnt(0)
	v_mfma_f32_16x16x32_bf16 v[84:87], v[120:123], v[68:71], v[84:87]
	ds_read_b128 v[120:123], v124
	v_or_b32_e32 v0, 0x80, v118
	s_nop 5
	v_mul_f32_e32 v84, 0x3fb8aa3b, v84
	s_waitcnt lgkmcnt(0)
	v_mfma_f32_16x16x32_bf16 v[80:83], v[120:123], v[80:83], 0
	ds_read_b128 v[120:123], v124 offset:64
	s_waitcnt lgkmcnt(0)
	v_mfma_f32_16x16x32_bf16 v[76:79], v[120:123], v[76:79], v[80:83]
	s_nop 4
	ds_read_b128 v[80:83], v124 offset:128
	s_waitcnt lgkmcnt(0)
	v_mfma_f32_16x16x32_bf16 v[72:75], v[80:83], v[72:75], v[76:79]
	s_nop 2
	ds_read_b128 v[76:79], v124 offset:192
	s_waitcnt lgkmcnt(0)
	v_mfma_f32_16x16x32_bf16 v[68:71], v[76:79], v[68:71], v[72:75]
	s_nop 2
	v_lshlrev_b32_e32 v72, 2, v116
	v_or_b32_e32 v2, s13, v72
	v_sub_u32_e32 v73, v0, v72
	v_cmp_lt_i32_e64 s[0:1], s33, v2
	v_cmp_gt_u32_e32 vcc, s29, v73
	s_or_b64 s[0:1], s[6:7], s[0:1]
	v_add_u32_e32 v79, s13, v0
	s_and_b64 vcc, vcc, s[0:1]
	v_mul_f32_e32 v73, 0x3fb8aa3b, v108
	v_sub_u32_e32 v0, v72, v0
	v_cmp_lt_i32_e64 s[0:1], s53, v2
	v_cndmask_b32_e32 v80, v228, v73, vcc
	v_cmp_lt_u32_e32 vcc, s28, v0
	s_or_b64 s[0:1], s[6:7], s[0:1]
	v_or_b32_e32 v73, 2, v2
	s_and_b64 vcc, vcc, s[0:1]
	v_mul_f32_e32 v0, 0x3fb8aa3b, v109
	v_sub_u32_e32 v74, v79, v73
	v_cmp_lt_i32_e64 s[0:1], s33, v73
	v_cndmask_b32_e32 v81, v228, v0, vcc
	v_cmp_gt_u32_e32 vcc, s29, v74
	s_or_b64 s[0:1], s[6:7], s[0:1]
	s_and_b64 vcc, vcc, s[0:1]
	v_mul_f32_e32 v73, 0x3fb8aa3b, v110
	v_cndmask_b32_e32 v82, v228, v73, vcc
	v_or_b32_e32 v73, 3, v2
	v_sub_u32_e32 v74, v79, v73
	v_cmp_lt_i32_e64 s[0:1], s33, v73
	v_cmp_gt_u32_e32 vcc, s29, v74
	s_or_b64 s[0:1], s[6:7], s[0:1]
	s_and_b64 vcc, vcc, s[0:1]
	v_mul_f32_e32 v73, 0x3fb8aa3b, v111
	v_or_b32_e32 v78, s25, v72
	v_cndmask_b32_e32 v83, v228, v73, vcc
	v_sub_u32_e32 v73, v79, v78
	v_cmp_lt_i32_e64 s[0:1], s33, v78
	v_cmp_gt_u32_e32 vcc, s29, v73
	s_or_b64 s[0:1], s[6:7], s[0:1]
	s_and_b64 vcc, vcc, s[0:1]
	v_mul_f32_e32 v73, 0x3fb8aa3b, v112
	v_cndmask_b32_e32 v108, v228, v73, vcc
	v_sub_u32_e32 v73, v78, v79
	v_cmp_lt_i32_e64 s[0:1], s53, v78
	v_cmp_lt_u32_e32 vcc, s28, v73
	s_or_b64 s[0:1], s[6:7], s[0:1]
	s_and_b64 vcc, vcc, s[0:1]
	v_mul_f32_e32 v73, 0x3fb8aa3b, v113
	v_cndmask_b32_e32 v109, v228, v73, vcc
	v_or_b32_e32 v73, 2, v78
	v_sub_u32_e32 v74, v79, v73
	v_cmp_lt_i32_e64 s[0:1], s33, v73
	v_cmp_gt_u32_e32 vcc, s29, v74
	s_or_b64 s[0:1], s[6:7], s[0:1]
	s_and_b64 vcc, vcc, s[0:1]
	v_mul_f32_e32 v73, 0x3fb8aa3b, v114
	v_cndmask_b32_e32 v110, v228, v73, vcc
	v_or_b32_e32 v73, 3, v78
	v_sub_u32_e32 v74, v79, v73
	v_cmp_lt_i32_e64 s[0:1], s33, v73
	v_cmp_gt_u32_e32 vcc, s29, v74
	s_or_b64 s[0:1], s[6:7], s[0:1]
	s_and_b64 vcc, vcc, s[0:1]
	v_mul_f32_e32 v73, 0x3fb8aa3b, v115
	v_or_b32_e32 v74, s24, v72
	v_cndmask_b32_e32 v111, v228, v73, vcc
	v_sub_u32_e32 v73, v79, v74
	v_cmp_lt_i32_e64 s[0:1], s33, v74
	v_cmp_gt_u32_e32 vcc, s29, v73
	s_or_b64 s[0:1], s[6:7], s[0:1]
	s_and_b64 vcc, vcc, s[0:1]
	v_mul_f32_e32 v73, 0x3fb8aa3b, v104
	v_cndmask_b32_e32 v104, v228, v73, vcc
	v_sub_u32_e32 v73, v74, v79
	v_cmp_lt_i32_e64 s[0:1], s53, v74
	v_cmp_lt_u32_e32 vcc, s28, v73
	s_or_b64 s[0:1], s[6:7], s[0:1]
	s_and_b64 vcc, vcc, s[0:1]
	v_mul_f32_e32 v73, 0x3fb8aa3b, v105
	v_cndmask_b32_e32 v105, v228, v73, vcc
	v_or_b32_e32 v73, 2, v74
	v_sub_u32_e32 v75, v79, v73
	v_cmp_lt_i32_e64 s[0:1], s33, v73
	v_cmp_gt_u32_e32 vcc, s29, v75
	s_or_b64 s[0:1], s[6:7], s[0:1]
	s_and_b64 vcc, vcc, s[0:1]
	v_mul_f32_e32 v73, 0x3fb8aa3b, v106
	v_cndmask_b32_e32 v106, v228, v73, vcc
	v_or_b32_e32 v73, 3, v74
	v_sub_u32_e32 v75, v79, v73
	v_cmp_lt_i32_e64 s[0:1], s33, v73
	v_cmp_gt_u32_e32 vcc, s29, v75
	s_or_b64 s[0:1], s[6:7], s[0:1]
	s_and_b64 vcc, vcc, s[0:1]
	v_mul_f32_e32 v73, 0x3fb8aa3b, v107
	v_or_b32_e32 v77, s23, v72
	v_cndmask_b32_e32 v107, v228, v73, vcc
	v_sub_u32_e32 v73, v79, v77
	v_cmp_lt_i32_e64 s[0:1], s33, v77
	v_cmp_gt_u32_e32 vcc, s29, v73
	s_or_b64 s[0:1], s[6:7], s[0:1]
	s_and_b64 vcc, vcc, s[0:1]
	v_mul_f32_e32 v73, 0x3fb8aa3b, v100
	v_cndmask_b32_e32 v112, v228, v73, vcc
	v_sub_u32_e32 v73, v77, v79
	v_cmp_lt_i32_e64 s[0:1], s53, v77
	v_cmp_lt_u32_e32 vcc, s28, v73
	s_or_b64 s[0:1], s[6:7], s[0:1]
	s_and_b64 vcc, vcc, s[0:1]
	v_mul_f32_e32 v73, 0x3fb8aa3b, v101
	v_cndmask_b32_e32 v113, v228, v73, vcc
	v_or_b32_e32 v73, 2, v77
	v_sub_u32_e32 v75, v79, v73
	v_cmp_lt_i32_e64 s[0:1], s33, v73
	v_cmp_gt_u32_e32 vcc, s29, v75
	s_or_b64 s[0:1], s[6:7], s[0:1]
	s_and_b64 vcc, vcc, s[0:1]
	v_mul_f32_e32 v73, 0x3fb8aa3b, v102
	v_cndmask_b32_e32 v114, v228, v73, vcc
	v_or_b32_e32 v73, 3, v77
	v_sub_u32_e32 v75, v79, v73
	v_cmp_lt_i32_e64 s[0:1], s33, v73
	v_cmp_gt_u32_e32 vcc, s29, v75
	s_or_b64 s[0:1], s[6:7], s[0:1]
	s_and_b64 vcc, vcc, s[0:1]
	v_mul_f32_e32 v73, 0x3fb8aa3b, v103
	v_cndmask_b32_e32 v115, v228, v73, vcc
	v_or_b32_e32 v73, s22, v72
	v_sub_u32_e32 v75, v79, v73
	v_cmp_lt_i32_e64 s[0:1], s33, v73
	v_cmp_gt_u32_e32 vcc, s29, v75
	s_or_b64 s[0:1], s[6:7], s[0:1]
	s_and_b64 vcc, vcc, s[0:1]
	v_mul_f32_e32 v75, 0x3fb8aa3b, v96
	v_cndmask_b32_e32 v96, v228, v75, vcc
	v_sub_u32_e32 v75, v73, v79
	v_cmp_lt_i32_e64 s[0:1], s53, v73
	v_cmp_lt_u32_e32 vcc, s28, v75
	s_or_b64 s[0:1], s[6:7], s[0:1]
	s_and_b64 vcc, vcc, s[0:1]
	v_mul_f32_e32 v75, 0x3fb8aa3b, v97
	v_cndmask_b32_e32 v97, v228, v75, vcc
	v_or_b32_e32 v75, 2, v73
	v_sub_u32_e32 v76, v79, v75
	v_cmp_lt_i32_e64 s[0:1], s33, v75
	v_cmp_gt_u32_e32 vcc, s29, v76
	s_or_b64 s[0:1], s[6:7], s[0:1]
	s_and_b64 vcc, vcc, s[0:1]
; __device__ __forceinline__ void dilated_item(const Params& p, int item, int next, u32x4 (&pk)[8], u32x4 (&pv)[8], LAS unsigned char* lds) {
;     ...
; #pragma unroll
;     for (int tt = 0; tt < 9; ++tt)
; #pragma unroll
;         for (int rr = 0; rr < 4; ++rr) {
;             const int kj = 16 * (w + tt) + 4 * g + rr, diff = qi - kj;
;             const bool valid = (diff >= 0) && (diff <= 128) && (blk > 0 || kj >= 128);
;             const float s = valid ? sc[tt][rr] * LOG2E : -1e30f;
;             sc[tt][rr] = s; mx = fmaxf(mx, s);
;         }
;     mx = fmaxf(mx, __shfl_xor(mx, 16)); mx = fmaxf(mx, __shfl_xor(mx, 32));
	v_mul_f32_e32 v75, 0x3fb8aa3b, v98
	v_cndmask_b32_e32 v98, v228, v75, vcc
	v_or_b32_e32 v75, 3, v73
	v_sub_u32_e32 v76, v79, v75
	v_cmp_lt_i32_e64 s[0:1], s33, v75
	v_cmp_gt_u32_e32 vcc, s29, v76
	s_or_b64 s[0:1], s[6:7], s[0:1]
	s_and_b64 vcc, vcc, s[0:1]
	v_mul_f32_e32 v75, 0x3fb8aa3b, v99
	v_or_b32_e32 v76, s18, v72
	v_cndmask_b32_e32 v119, v228, v75, vcc
	v_sub_u32_e32 v75, v79, v76
	v_cmp_lt_i32_e64 s[0:1], s33, v76
	v_cmp_gt_u32_e32 vcc, s29, v75
	s_or_b64 s[0:1], s[6:7], s[0:1]
	s_and_b64 vcc, vcc, s[0:1]
	v_mul_f32_e32 v75, 0x3fb8aa3b, v92
	v_cndmask_b32_e32 v120, v228, v75, vcc
	v_sub_u32_e32 v75, v76, v79
	v_cmp_lt_i32_e64 s[0:1], s53, v76
	v_max3_f32 v0, v80, s49, v81
	v_cmp_lt_u32_e32 vcc, s28, v75
	s_or_b64 s[0:1], s[6:7], s[0:1]
	v_max3_f32 v0, v0, v82, v83
	s_and_b64 vcc, vcc, s[0:1]
	v_mul_f32_e32 v75, 0x3fb8aa3b, v93
	v_max3_f32 v0, v0, v108, v109
	v_cndmask_b32_e32 v121, v228, v75, vcc
	v_or_b32_e32 v75, 2, v76
	v_max3_f32 v0, v0, v110, v111
	v_sub_u32_e32 v92, v79, v75
	v_cmp_lt_i32_e64 s[0:1], s33, v75
	v_max3_f32 v0, v0, v104, v105
	v_cmp_gt_u32_e32 vcc, s29, v92
	s_or_b64 s[0:1], s[6:7], s[0:1]
	v_max3_f32 v0, v0, v106, v107
	s_and_b64 vcc, vcc, s[0:1]
	v_mul_f32_e32 v75, 0x3fb8aa3b, v94
	v_max3_f32 v0, v0, v112, v113
	v_cndmask_b32_e32 v122, v228, v75, vcc
	v_or_b32_e32 v75, 3, v76
	v_max3_f32 v0, v0, v114, v115
	v_sub_u32_e32 v92, v79, v75
	v_cmp_lt_i32_e64 s[0:1], s33, v75
	v_max3_f32 v0, v0, v96, v97
	v_cmp_gt_u32_e32 vcc, s29, v92
	s_or_b64 s[0:1], s[6:7], s[0:1]
	v_max3_f32 v0, v0, v98, v119
	s_and_b64 vcc, vcc, s[0:1]
	v_mul_f32_e32 v75, 0x3fb8aa3b, v95
	v_max3_f32 v0, v0, v120, v121
	v_cndmask_b32_e32 v123, v228, v75, vcc
	v_max3_f32 v75, v0, v122, v123
	v_or_b32_e32 v0, s17, v72
	v_sub_u32_e32 v92, v79, v0
	v_cmp_lt_i32_e64 s[0:1], s33, v0
	v_cmp_gt_u32_e32 vcc, s29, v92
	s_or_b64 s[0:1], s[6:7], s[0:1]
	s_and_b64 vcc, vcc, s[0:1]
	v_sub_u32_e32 v92, v0, v79
	v_cmp_lt_i32_e64 s[0:1], s53, v0
	v_cndmask_b32_e32 v88, v228, v88, vcc
	v_cmp_lt_u32_e32 vcc, s28, v92
	s_or_b64 s[0:1], s[6:7], s[0:1]
	v_or_b32_e32 v92, 2, v0
	s_and_b64 vcc, vcc, s[0:1]
	v_sub_u32_e32 v93, v79, v92
	v_cmp_lt_i32_e64 s[0:1], s33, v92
	v_cndmask_b32_e32 v89, v228, v89, vcc
	v_cmp_gt_u32_e32 vcc, s29, v93
	s_or_b64 s[0:1], s[6:7], s[0:1]
	v_or_b32_e32 v92, 3, v0
	s_and_b64 vcc, vcc, s[0:1]
	v_sub_u32_e32 v93, v79, v92
	v_cmp_lt_i32_e64 s[0:1], s33, v92
	v_cndmask_b32_e32 v90, v228, v90, vcc
	v_cmp_gt_u32_e32 vcc, s29, v93
	s_or_b64 s[0:1], s[6:7], s[0:1]
	s_and_b64 vcc, vcc, s[0:1]
	v_max3_f32 v75, v75, v88, v89
	v_cndmask_b32_e32 v124, v228, v91, vcc
	v_max3_f32 v91, v75, v90, v124
	v_or_b32_e32 v75, s16, v72
	v_sub_u32_e32 v92, v79, v75
	v_cmp_lt_i32_e64 s[0:1], s33, v75
	v_cmp_gt_u32_e32 vcc, s29, v92
	s_or_b64 s[0:1], s[6:7], s[0:1]
	s_and_b64 vcc, vcc, s[0:1]
	v_cndmask_b32_e32 v125, v228, v84, vcc
	v_sub_u32_e32 v84, v75, v79
	v_cmp_lt_i32_e64 s[0:1], s53, v75
	v_cmp_lt_u32_e32 vcc, s28, v84
	s_or_b64 s[0:1], s[6:7], s[0:1]
	s_and_b64 vcc, vcc, s[0:1]
	v_mul_f32_e32 v84, 0x3fb8aa3b, v85
	v_cndmask_b32_e32 v126, v228, v84, vcc
	v_or_b32_e32 v85, 2, v75
	v_max3_f32 v84, v91, v125, v126
	v_sub_u32_e32 v91, v79, v85
	v_cmp_lt_i32_e64 s[0:1], s33, v85
	v_cmp_gt_u32_e32 vcc, s29, v91
	s_or_b64 s[0:1], s[6:7], s[0:1]
	s_and_b64 vcc, vcc, s[0:1]
	v_mul_f32_e32 v85, 0x3fb8aa3b, v86
	v_cndmask_b32_e32 v127, v228, v85, vcc
	v_or_b32_e32 v85, 3, v75
	v_sub_u32_e32 v86, v79, v85
	v_cmp_lt_i32_e64 s[0:1], s33, v85
	v_cmp_gt_u32_e32 vcc, s29, v86
	s_or_b64 s[0:1], s[6:7], s[0:1]
	s_and_b64 vcc, vcc, s[0:1]
	v_mul_f32_e32 v85, 0x3fb8aa3b, v87
	v_or_b32_e32 v72, s15, v72
	v_cndmask_b32_e32 v128, v228, v85, vcc
	v_sub_u32_e32 v85, v79, v72
	v_cmp_lt_i32_e64 s[0:1], s33, v72
	v_cmp_gt_u32_e32 vcc, s29, v85
	s_or_b64 s[0:1], s[6:7], s[0:1]
	s_and_b64 vcc, vcc, s[0:1]
	v_mul_f32_e32 v68, 0x3fb8aa3b, v68
	v_sub_u32_e32 v85, v72, v79
	v_cmp_lt_i32_e64 s[0:1], s53, v72
	v_cndmask_b32_e32 v68, v228, v68, vcc
	v_cmp_lt_u32_e32 vcc, s28, v85
	s_or_b64 s[0:1], s[6:7], s[0:1]
	s_and_b64 vcc, vcc, s[0:1]
	v_mul_f32_e32 v69, 0x3fb8aa3b, v69
	v_max3_f32 v84, v84, v127, v128
	v_cndmask_b32_e32 v129, v228, v69, vcc
	v_max3_f32 v69, v84, v68, v129
	v_or_b32_e32 v84, 2, v72
	v_sub_u32_e32 v85, v79, v84
	v_cmp_lt_i32_e64 s[0:1], s33, v84
	v_cmp_gt_u32_e32 vcc, s29, v85
	s_or_b64 s[0:1], s[6:7], s[0:1]
	v_or_b32_e32 v84, 3, v72
	s_and_b64 vcc, vcc, s[0:1]
	v_mul_f32_e32 v70, 0x3fb8aa3b, v70
	v_sub_u32_e32 v79, v79, v84
	v_cmp_lt_i32_e64 s[0:1], s33, v84
	v_cndmask_b32_e32 v70, v228, v70, vcc
	v_cmp_gt_u32_e32 vcc, s29, v79
	s_or_b64 s[0:1], s[6:7], s[0:1]
	s_and_b64 vcc, vcc, s[0:1]
	v_mul_f32_e32 v71, 0x3fb8aa3b, v71
	v_cndmask_b32_e32 v71, v228, v71, vcc
	v_cmp_lt_i32_e32 vcc, v218, v216
	v_max3_f32 v69, v69, v70, v71
	s_cmp_eq_u32 s4, 1
	v_cndmask_b32_e32 v79, v215, v218, vcc
	v_lshlrev_b32_e32 v130, 2, v79
	ds_bpermute_b32 v79, v130, v69
	v_cmp_lt_i32_e32 vcc, v217, v216
	s_waitcnt lgkmcnt(0)
	v_max_f32_e32 v79, v79, v79
	v_max_f32_e32 v69, v69, v79
	v_cndmask_b32_e32 v79, v215, v217, vcc
	v_lshlrev_b32_e32 v131, 2, v79
	ds_bpermute_b32 v79, v131, v69
	s_waitcnt lgkmcnt(0)
; __device__ __forceinline__ unsigned cvt_pk_bf16(float lo, float hi) { const f32x2v v = {lo, hi}; const b16x2v r = __builtin_convertvector(v, b16x2v); return __builtin_bit_cast(unsigned, r); }
; __device__ __forceinline__ float fexp2(float x) { return __builtin_amdgcn_exp2f(x); }
; __device__ __forceinline__ f32x4 mfma16(bf16x8 a, bf16x8 b, f32x4 c) { return __builtin_amdgcn_mfma_f32_16x16x32_bf16(a, b, c, 0, 0, 0); }
; __device__ __forceinline__ void dilated_item(const Params& p, int item, int next, u32x4 (&pk)[8], u32x4 (&pv)[8], LAS unsigned char* lds) {
;     ...
;     float sum = 0.f;
; #pragma unroll
;     for (int tt = 0; tt < 9; ++tt)
; #pragma unroll
;         for (int rr = 0; rr < 4; ++rr) { const float e = fexp2(sc[tt][rr] - mx); sc[tt][rr] = e; sum += e; }
;     sum += __shfl_xor(sum, 16); sum += __shfl_xor(sum, 32);
;     f32x4 ot[8];
; #pragma unroll
;     for (int c = 0; c < 8; ++c) ot[c] = (f32x4){0.f, 0.f, 0.f, 0.f};
; #pragma unroll
;     for (int s5 = 0; s5 < 5; ++s5) {
;         const int ta = w + 2 * s5, tb = (s5 < 4) ? ta + 1 : ta;
;         u32x4 pw; pw.x = cvt_pk_bf16(sc[2 * s5][0], sc[2 * s5][1]); pw.y = cvt_pk_bf16(sc[2 * s5][2], sc[2 * s5][3]);
;         if (s5 < 4) { pw.z = cvt_pk_bf16(sc[(2 * s5 + 1) % 9][0], sc[(2 * s5 + 1) % 9][1]); pw.w = cvt_pk_bf16(sc[(2 * s5 + 1) % 9][2], sc[(2 * s5 + 1) % 9][3]); } else { pw.z = 0u; pw.w = 0u; }
;         const bf16x8 pf = __builtin_bit_cast(bf16x8, pw);
;         const unsigned aA = lbase + KV_BUF + (unsigned)((16 * ta + 4 * g + (idx >> 2)) * KV_STRIDE + 8 * (idx & 3));
;         const unsigned aB = lbase + KV_BUF + (unsigned)((16 * tb + 4 * g + (idx >> 2)) * KV_STRIDE + 8 * (idx & 3));
;         bf16x8 vf[4];
;         tr_frag4(aA, aB, vf);
; #pragma unroll
;         for (int c = 0; c < 4; ++c) ot[c] = mfma16(vf[c], pf, ot[c]);
;         tr_frag4(aA + 128, aB + 128, vf);
; #pragma unroll
;         for (int c = 0; c < 4; ++c) ot[4 + c] = mfma16(vf[c], pf, ot[4 + c]);
	v_max_f32_e32 v79, v79, v79
	v_max_f32_e32 v69, v69, v79
	v_sub_f32_e32 v79, v80, v69
	v_exp_f32_e32 v132, v79
	v_sub_f32_e32 v80, v81, v69
	v_exp_f32_e32 v133, v80
	v_sub_f32_e32 v80, v82, v69
	v_exp_f32_e32 v134, v80
	v_sub_f32_e32 v80, v83, v69
	v_exp_f32_e32 v135, v80
	v_sub_f32_e32 v80, v108, v69
	v_add_f32_e32 v79, 0, v132
	v_exp_f32_e32 v136, v80
	v_sub_f32_e32 v80, v109, v69
	v_add_f32_e32 v79, v133, v79
	v_exp_f32_e32 v137, v80
	v_sub_f32_e32 v80, v110, v69
	v_add_f32_e32 v79, v134, v79
	v_exp_f32_e32 v138, v80
	v_sub_f32_e32 v80, v111, v69
	v_add_f32_e32 v79, v135, v79
	v_exp_f32_e32 v111, v80
	v_sub_f32_e32 v80, v104, v69
	v_add_f32_e32 v79, v136, v79
	v_exp_f32_e32 v99, v80
	v_sub_f32_e32 v80, v105, v69
	v_add_f32_e32 v79, v137, v79
	v_exp_f32_e32 v100, v80
	v_sub_f32_e32 v80, v106, v69
	v_add_f32_e32 v79, v138, v79
	v_exp_f32_e32 v101, v80
	v_sub_f32_e32 v80, v107, v69
	v_add_f32_e32 v79, v111, v79
	v_exp_f32_e32 v102, v80
	v_sub_f32_e32 v80, v112, v69
	v_add_f32_e32 v79, v99, v79
	v_exp_f32_e32 v103, v80
	v_sub_f32_e32 v80, v113, v69
	v_add_f32_e32 v79, v100, v79
	v_exp_f32_e32 v104, v80
	v_sub_f32_e32 v80, v114, v69
	v_add_f32_e32 v79, v101, v79
	v_exp_f32_e32 v105, v80
	v_sub_f32_e32 v80, v115, v69
	v_add_f32_e32 v79, v102, v79
	v_exp_f32_e32 v106, v80
	v_sub_f32_e32 v80, v96, v69
	v_add_f32_e32 v79, v103, v79
	v_exp_f32_e32 v91, v80
	v_sub_f32_e32 v80, v97, v69
	v_add_f32_e32 v79, v104, v79
	v_exp_f32_e32 v92, v80
	v_sub_f32_e32 v80, v98, v69
	v_add_f32_e32 v79, v105, v79
	v_exp_f32_e32 v93, v80
	v_sub_f32_e32 v80, v119, v69
	v_add_f32_e32 v79, v106, v79
	v_exp_f32_e32 v94, v80
	v_sub_f32_e32 v80, v120, v69
	v_add_f32_e32 v79, v91, v79
	v_exp_f32_e32 v95, v80
	v_sub_f32_e32 v80, v121, v69
	v_add_f32_e32 v79, v92, v79
	v_exp_f32_e32 v96, v80
	v_sub_f32_e32 v80, v122, v69
	v_add_f32_e32 v79, v93, v79
	v_exp_f32_e32 v97, v80
	v_sub_f32_e32 v80, v123, v69
	v_add_f32_e32 v79, v94, v79
	v_exp_f32_e32 v98, v80
	v_sub_f32_e32 v80, v88, v69
	v_add_f32_e32 v79, v95, v79
	v_exp_f32_e32 v83, v80
	v_sub_f32_e32 v80, v89, v69
	v_add_f32_e32 v79, v96, v79
	v_exp_f32_e32 v84, v80
	v_sub_f32_e32 v80, v90, v69
	v_add_f32_e32 v79, v97, v79
	v_exp_f32_e32 v85, v80
	v_sub_f32_e32 v80, v124, v69
	v_add_f32_e32 v79, v98, v79
	v_exp_f32_e32 v86, v80
	v_sub_f32_e32 v80, v125, v69
	v_add_f32_e32 v79, v83, v79
	v_exp_f32_e32 v87, v80
	v_sub_f32_e32 v80, v126, v69
	v_add_f32_e32 v79, v84, v79
	v_exp_f32_e32 v88, v80
	v_sub_f32_e32 v80, v127, v69
	v_add_f32_e32 v79, v85, v79
	v_exp_f32_e32 v89, v80
	v_sub_f32_e32 v80, v128, v69
	v_add_f32_e32 v79, v86, v79
	v_exp_f32_e32 v90, v80
	v_add_f32_e32 v79, v87, v79
	v_add_f32_e32 v79, v88, v79
	v_add_f32_e32 v79, v89, v79
	v_sub_f32_e32 v68, v68, v69
	v_add_f32_e32 v80, v90, v79
	v_exp_f32_e32 v79, v68
	v_sub_f32_e32 v70, v70, v69
	v_exp_f32_e32 v81, v70
	v_sub_f32_e32 v70, v71, v69
	v_add_f32_e32 v68, v79, v80
	v_sub_f32_e32 v80, v129, v69
	v_exp_f32_e32 v80, v80
	v_exp_f32_e32 v82, v70
	v_lshrrev_b32_e32 v107, 2, v118
	v_cvt_pk_bf16_f32 v108, v132, v133
	v_add_f32_e32 v68, v80, v68
	v_add_f32_e32 v68, v81, v68
	v_add_f32_e32 v68, v82, v68
	ds_bpermute_b32 v70, v130, v68
	v_cvt_pk_bf16_f32 v109, v134, v135
	v_cvt_pk_bf16_f32 v110, v136, v137
	v_cvt_pk_bf16_f32 v111, v138, v111
	v_cvt_pk_bf16_f32 v101, v101, v102
	s_waitcnt lgkmcnt(0)
	v_add_f32_e32 v70, v68, v70
	v_and_b32_e32 v68, 24, v1
	v_or_b32_e32 v1, v2, v107
	v_or_b32_e32 v2, v78, v107
	ds_bpermute_b32 v71, v131, v70
	v_mad_u64_u32 v[130:131], s[0:1], v1, s99, v[68:69]
	v_mad_u64_u32 v[132:133], s[0:1], v2, s99, v[68:69]
	v_add_u32_e32 v1, s11, v130
	v_add_u32_e32 v2, s11, v132
	ds_read_b64_tr_b16 v[126:127], v1
	ds_read_b64_tr_b16 v[122:123], v1 offset:32
	ds_read_b64_tr_b16 v[118:119], v1 offset:64
	ds_read_b64_tr_b16 v[112:113], v1 offset:96
	ds_read_b64_tr_b16 v[128:129], v2
	ds_read_b64_tr_b16 v[124:125], v2 offset:32
	ds_read_b64_tr_b16 v[120:121], v2 offset:64
	ds_read_b64_tr_b16 v[114:115], v2 offset:96
	s_waitcnt lgkmcnt(0)
	v_add_u32_e32 v1, s14, v130
	v_mfma_f32_16x16x32_bf16 v[126:129], v[126:129], v[108:111], 0
	v_add_u32_e32 v2, s14, v132
	ds_read_b64_tr_b16 v[142:143], v1
	ds_read_b64_tr_b16 v[138:139], v1 offset:32
	ds_read_b64_tr_b16 v[134:135], v1 offset:64
	ds_read_b64_tr_b16 v[130:131], v1 offset:96
	ds_read_b64_tr_b16 v[144:145], v2
	ds_read_b64_tr_b16 v[140:141], v2 offset:32
	ds_read_b64_tr_b16 v[136:137], v2 offset:64
	ds_read_b64_tr_b16 v[132:133], v2 offset:96
	s_waitcnt lgkmcnt(0)
	v_or_b32_e32 v1, v74, v107
	v_mfma_f32_16x16x32_bf16 v[122:125], v[122:125], v[108:111], 0
	v_or_b32_e32 v2, v77, v107
	v_cvt_pk_bf16_f32 v102, v103, v104
	v_cvt_pk_bf16_f32 v103, v105, v106
	v_mfma_f32_16x16x32_bf16 v[118:121], v[118:121], v[108:111], 0
	v_mad_u64_u32 v[104:105], s[0:1], v1, s99, v[68:69]
	v_mad_u64_u32 v[158:159], s[0:1], v2, s99, v[68:69]
	v_mfma_f32_16x16x32_bf16 v[112:115], v[112:115], v[108:111], 0
	v_cvt_pk_bf16_f32 v100, v99, v100
	v_add_u32_e32 v1, s11, v104
	v_add_u32_e32 v2, s11, v158
	v_mfma_f32_16x16x32_bf16 v[142:145], v[142:145], v[108:111], 0
	v_cvt_pk_bf16_f32 v92, v91, v92
	v_cvt_pk_bf16_f32 v93, v93, v94
	v_cvt_pk_bf16_f32 v94, v95, v96
	v_mfma_f32_16x16x32_bf16 v[138:141], v[138:141], v[108:111], 0
	v_cvt_pk_bf16_f32 v95, v97, v98
	v_or_b32_e32 v0, v0, v107
	v_cvt_pk_bf16_f32 v84, v83, v84
	v_mfma_f32_16x16x32_bf16 v[134:137], v[134:137], v[108:111], 0
	v_cvt_pk_bf16_f32 v85, v85, v86
	v_cvt_pk_bf16_f32 v86, v87, v88
	v_cvt_pk_bf16_f32 v87, v89, v90
	v_mfma_f32_16x16x32_bf16 v[108:111], v[130:133], v[108:111], 0
	ds_read_b64_tr_b16 v[154:155], v1
	ds_read_b64_tr_b16 v[150:151], v1 offset:32
	ds_read_b64_tr_b16 v[146:147], v1 offset:64
	ds_read_b64_tr_b16 v[130:131], v1 offset:96
	ds_read_b64_tr_b16 v[156:157], v2
	ds_read_b64_tr_b16 v[152:153], v2 offset:32
	ds_read_b64_tr_b16 v[148:149], v2 offset:64
	ds_read_b64_tr_b16 v[132:133], v2 offset:96
	s_waitcnt lgkmcnt(0)
; __device__ __forceinline__ unsigned cvt_pk_bf16(float lo, float hi) { const f32x2v v = {lo, hi}; const b16x2v r = __builtin_convertvector(v, b16x2v); return __builtin_bit_cast(unsigned, r); }
; __device__ __forceinline__ f32x4 mfma16(bf16x8 a, bf16x8 b, f32x4 c) { return __builtin_amdgcn_mfma_f32_16x16x32_bf16(a, b, c, 0, 0, 0); }
; __device__ __forceinline__ void dilated_item(const Params& p, int item, int next, u32x4 (&pk)[8], u32x4 (&pv)[8], LAS unsigned char* lds) {
;     ...
;     for (int s5 = 0; s5 < 5; ++s5) {
;         const int ta = w + 2 * s5, tb = (s5 < 4) ? ta + 1 : ta;
;         u32x4 pw; pw.x = cvt_pk_bf16(sc[2 * s5][0], sc[2 * s5][1]); pw.y = cvt_pk_bf16(sc[2 * s5][2], sc[2 * s5][3]);
;         if (s5 < 4) { pw.z = cvt_pk_bf16(sc[(2 * s5 + 1) % 9][0], sc[(2 * s5 + 1) % 9][1]); pw.w = cvt_pk_bf16(sc[(2 * s5 + 1) % 9][2], sc[(2 * s5 + 1) % 9][3]); } else { pw.z = 0u; pw.w = 0u; }
;         const bf16x8 pf = __builtin_bit_cast(bf16x8, pw);
;         const unsigned aA = lbase + KV_BUF + (unsigned)((16 * ta + 4 * g + (idx >> 2)) * KV_STRIDE + 8 * (idx & 3));
;         const unsigned aB = lbase + KV_BUF + (unsigned)((16 * tb + 4 * g + (idx >> 2)) * KV_STRIDE + 8 * (idx & 3));
;         bf16x8 vf[4];
;         tr_frag4(aA, aB, vf);
; #pragma unroll
;         for (int c = 0; c < 4; ++c) ot[c] = mfma16(vf[c], pf, ot[c]);
;         tr_frag4(aA + 128, aB + 128, vf);
; #pragma unroll
;         for (int c = 0; c < 4; ++c) ot[4 + c] = mfma16(vf[c], pf, ot[4 + c]);
	v_add_u32_e32 v1, s14, v104
	v_add_u32_e32 v2, s14, v158
	v_mfma_f32_16x16x32_bf16 v[126:129], v[154:157], v[100:103], v[126:129]
	v_or_b32_e32 v72, v72, v107
	v_mfma_f32_16x16x32_bf16 v[122:125], v[150:153], v[100:103], v[122:125]
	v_mfma_f32_16x16x32_bf16 v[118:121], v[146:149], v[100:103], v[118:121]
	v_mfma_f32_16x16x32_bf16 v[112:115], v[130:133], v[100:103], v[112:115]
	ds_read_b64_tr_b16 v[154:155], v1
	ds_read_b64_tr_b16 v[150:151], v1 offset:32
	ds_read_b64_tr_b16 v[146:147], v1 offset:64
	ds_read_b64_tr_b16 v[130:131], v1 offset:96
	ds_read_b64_tr_b16 v[156:157], v2
	ds_read_b64_tr_b16 v[152:153], v2 offset:32
	ds_read_b64_tr_b16 v[148:149], v2 offset:64
	ds_read_b64_tr_b16 v[132:133], v2 offset:96
	s_waitcnt lgkmcnt(0)
	v_or_b32_e32 v1, v73, v107
	v_or_b32_e32 v2, v76, v107
	v_mfma_f32_16x16x32_bf16 v[142:145], v[154:157], v[100:103], v[142:145]
	v_mad_u64_u32 v[104:105], s[0:1], v1, s99, v[68:69]
	v_mad_u64_u32 v[76:77], s[0:1], v2, s99, v[68:69]
	v_mfma_f32_16x16x32_bf16 v[138:141], v[150:153], v[100:103], v[138:141]
	v_add_u32_e32 v1, s11, v104
	v_add_u32_e32 v2, s11, v76
	v_mfma_f32_16x16x32_bf16 v[134:137], v[146:149], v[100:103], v[134:137]
	v_mfma_f32_16x16x32_bf16 v[100:103], v[130:133], v[100:103], v[108:111]
	ds_read_b64_tr_b16 v[146:147], v1
	ds_read_b64_tr_b16 v[130:131], v1 offset:32
	ds_read_b64_tr_b16 v[108:109], v1 offset:64
	ds_read_b64_tr_b16 v[96:97], v1 offset:96
	ds_read_b64_tr_b16 v[148:149], v2
	ds_read_b64_tr_b16 v[132:133], v2 offset:32
	ds_read_b64_tr_b16 v[110:111], v2 offset:64
	ds_read_b64_tr_b16 v[98:99], v2 offset:96
	s_waitcnt lgkmcnt(0)
	v_add_u32_e32 v1, s14, v104
	v_add_u32_e32 v2, s14, v76
	v_mfma_f32_16x16x32_bf16 v[126:129], v[146:149], v[92:95], v[126:129]
	v_mfma_f32_16x16x32_bf16 v[122:125], v[130:133], v[92:95], v[122:125]
	v_mfma_f32_16x16x32_bf16 v[108:111], v[108:111], v[92:95], v[118:121]
	v_mfma_f32_16x16x32_bf16 v[96:99], v[96:99], v[92:95], v[112:115]
	ds_read_b64_tr_b16 v[146:147], v1
	ds_read_b64_tr_b16 v[130:131], v1 offset:32
	ds_read_b64_tr_b16 v[118:119], v1 offset:64
	ds_read_b64_tr_b16 v[112:113], v1 offset:96
	ds_read_b64_tr_b16 v[148:149], v2
	ds_read_b64_tr_b16 v[132:133], v2 offset:32
	ds_read_b64_tr_b16 v[120:121], v2 offset:64
	ds_read_b64_tr_b16 v[114:115], v2 offset:96
	s_waitcnt lgkmcnt(0)
	v_or_b32_e32 v2, v75, v107
	v_mad_u64_u32 v[0:1], s[0:1], v0, s99, v[68:69]
	v_mfma_f32_16x16x32_bf16 v[142:145], v[146:149], v[92:95], v[142:145]
	v_mad_u64_u32 v[104:105], s[0:1], v2, s99, v[68:69]
	v_add_u32_e32 v1, s11, v0
	v_mfma_f32_16x16x32_bf16 v[130:133], v[130:133], v[92:95], v[138:141]
	v_add_u32_e32 v2, s11, v104
	v_add_u32_e32 v0, s14, v0
	v_mfma_f32_16x16x32_bf16 v[118:121], v[118:121], v[92:95], v[134:137]
	v_mfma_f32_16x16x32_bf16 v[92:95], v[112:115], v[92:95], v[100:103]
	ds_read_b64_tr_b16 v[112:113], v1
	ds_read_b64_tr_b16 v[100:101], v1 offset:32
	ds_read_b64_tr_b16 v[88:89], v1 offset:64
	ds_read_b64_tr_b16 v[74:75], v1 offset:96
	ds_read_b64_tr_b16 v[114:115], v2
	ds_read_b64_tr_b16 v[102:103], v2 offset:32
	ds_read_b64_tr_b16 v[90:91], v2 offset:64
	ds_read_b64_tr_b16 v[76:77], v2 offset:96
	s_waitcnt lgkmcnt(0)
	v_add_u32_e32 v1, s14, v104
	v_mov_b32_e32 v2, v3
	v_mfma_f32_16x16x32_bf16 v[112:115], v[112:115], v[84:87], v[126:129]
	v_mfma_f32_16x16x32_bf16 v[100:103], v[100:103], v[84:87], v[122:125]
	v_mfma_f32_16x16x32_bf16 v[88:91], v[88:91], v[84:87], v[108:111]
	v_mfma_f32_16x16x32_bf16 v[74:77], v[74:77], v[84:87], v[96:99]
	ds_read_b64_tr_b16 v[126:127], v0
	ds_read_b64_tr_b16 v[122:123], v0 offset:32
	ds_read_b64_tr_b16 v[108:109], v0 offset:64
	ds_read_b64_tr_b16 v[96:97], v0 offset:96
	ds_read_b64_tr_b16 v[128:129], v1
	ds_read_b64_tr_b16 v[124:125], v1 offset:32
	ds_read_b64_tr_b16 v[110:111], v1 offset:64
	ds_read_b64_tr_b16 v[98:99], v1 offset:96
	s_waitcnt lgkmcnt(0)
	v_cvt_pk_bf16_f32 v1, v81, v82
	v_mad_u64_u32 v[82:83], s[0:1], v72, s99, v[68:69]
	v_mfma_f32_16x16x32_bf16 v[126:129], v[126:129], v[84:87], v[142:145]
	v_add_u32_e32 v68, s11, v82
	v_cvt_pk_bf16_f32 v0, v79, v80
	v_mfma_f32_16x16x32_bf16 v[122:125], v[122:125], v[84:87], v[130:133]
	v_mfma_f32_16x16x32_bf16 v[108:111], v[108:111], v[84:87], v[118:121]
	v_mfma_f32_16x16x32_bf16 v[84:87], v[96:99], v[84:87], v[92:95]
	ds_read_b64_tr_b16 v[104:105], v68
	ds_read_b64_tr_b16 v[96:97], v68 offset:32
	ds_read_b64_tr_b16 v[92:93], v68 offset:64
	ds_read_b64_tr_b16 v[78:79], v68 offset:96
	ds_read_b64_tr_b16 v[106:107], v68
	ds_read_b64_tr_b16 v[98:99], v68 offset:32
	ds_read_b64_tr_b16 v[94:95], v68 offset:64
	ds_read_b64_tr_b16 v[80:81], v68 offset:96
	s_waitcnt lgkmcnt(0)
; __device__ __forceinline__ unsigned cvt_pk_bf16(float lo, float hi) { const f32x2v v = {lo, hi}; const b16x2v r = __builtin_convertvector(v, b16x2v); return __builtin_bit_cast(unsigned, r); }
; __device__ __forceinline__ float flog2(float x) { return __builtin_amdgcn_logf(x); }
; __device__ __forceinline__ f32x4 mfma16(bf16x8 a, bf16x8 b, f32x4 c) { return __builtin_amdgcn_mfma_f32_16x16x32_bf16(a, b, c, 0, 0, 0); }
; __device__ __forceinline__ void dilated_item(const Params& p, int item, int next, u32x4 (&pk)[8], u32x4 (&pv)[8], LAS unsigned char* lds) {
;     ...
; #pragma unroll
;         for (int c = 0; c < 4; ++c) ot[c] = mfma16(vf[c], pf, ot[c]);
;         tr_frag4(aA + 128, aB + 128, vf);
; #pragma unroll
;         for (int c = 0; c < 4; ++c) ot[4 + c] = mfma16(vf[c], pf, ot[4 + c]);
;     }
;     const float inv = 1.0f / sum;
;     const size_t tok = (size_t)(b * SEQ + qpos);
;     bf16_t* od = (bf16_t*)(ws + (pat == 0 ? OFF_B2 : (pat == 1 ? OFF_B2 + 32 * MiB : OFF_OD2)));
; #pragma unroll
;     for (int c = 0; c < 8; ++c) { u32x2 wv; wv.x = cvt_pk_bf16(ot[c][0] * inv, ot[c][1] * inv); wv.y = cvt_pk_bf16(ot[c][2] * inv, ot[c][3] * inv);
;         *(u32x2*)(od + tok * 1024 + head * 128 + 16 * c + 4 * g) = wv; }
;     if (g == 0) ((float*)(ws + OFF_LSE))[(size_t)pat * T_TOK * 8 + tok * 8 + head] = (mx + flog2(sum)) * LN2;
	v_add_u32_e32 v68, s14, v82
	v_mfma_f32_16x16x32_bf16 v[96:99], v[96:99], v[0:3], v[100:103]
	v_mfma_f32_16x16x32_bf16 v[88:91], v[92:95], v[0:3], v[88:91]
	v_mfma_f32_16x16x32_bf16 v[72:75], v[78:81], v[0:3], v[74:77]
	ds_read_b64_tr_b16 v[100:101], v68
	ds_read_b64_tr_b16 v[92:93], v68 offset:32
	ds_read_b64_tr_b16 v[80:81], v68 offset:64
	ds_read_b64_tr_b16 v[76:77], v68 offset:96
	ds_read_b64_tr_b16 v[102:103], v68
	ds_read_b64_tr_b16 v[94:95], v68 offset:32
	ds_read_b64_tr_b16 v[82:83], v68 offset:64
	ds_read_b64_tr_b16 v[78:79], v68 offset:96
	s_waitcnt lgkmcnt(0)
	s_waitcnt lgkmcnt(0)
	v_add_f32_e32 v68, v70, v71
	v_mfma_f32_16x16x32_bf16 v[104:107], v[104:107], v[0:3], v[112:115]
	v_mfma_f32_16x16x32_bf16 v[100:103], v[100:103], v[0:3], v[126:129]
	v_mfma_f32_16x16x32_bf16 v[92:95], v[92:95], v[0:3], v[122:125]
	v_mfma_f32_16x16x32_bf16 v[80:83], v[80:83], v[0:3], v[108:111]
	v_mfma_f32_16x16x32_bf16 v[76:79], v[76:79], v[0:3], v[84:87]
	v_div_scale_f32 v0, s[0:1], v68, v68, 1.0
	v_rcp_f32_e32 v1, v0
	s_mov_b32 s0, 0x6000000
	s_cselect_b32 s0, s0, 0x1b100000
	s_cmpk_gt_u32 s8, 0x3ff
	v_fma_f32 v2, -v0, v1, 1.0
	v_fmac_f32_e32 v1, v2, v1
	v_div_scale_f32 v2, vcc, 1.0, v68, 1.0
	v_mul_f32_e32 v70, v2, v1
	v_fma_f32 v71, -v0, v70, v2
	v_fmac_f32_e32 v70, v71, v1
	v_fma_f32 v0, -v0, v70, v2
	v_div_fmas_f32 v0, v0, v1, v70
	v_div_fixup_f32 v70, v0, v68, 1.0
	v_add_u32_e32 v0, s5, v117
	s_cselect_b32 s0, s0, 0x4000000
	v_ashrrev_i32_e32 v1, 31, v0
	s_add_u32 s0, s92, s0
	s_addc_u32 s1, s93, 0
	v_lshlrev_b64 v[84:85], 11, v[0:1]
	v_lshl_add_u64 v[84:85], s[0:1], 0, v[84:85]
	s_lshl_b32 s18, s12, 1
	v_lshl_add_u64 v[84:85], v[84:85], 0, s[18:19]
	v_lshlrev_b32_e32 v2, 3, v116
	v_pk_mul_f32 v[72:73], v[70:71], v[72:73] op_sel_hi:[0,1]
	v_pk_mul_f32 v[74:75], v[70:71], v[74:75] op_sel_hi:[0,1]
	v_lshl_add_u64 v[84:85], v[84:85], 0, v[2:3]
	v_cvt_pk_bf16_f32 v72, v72, v73
	v_cvt_pk_bf16_f32 v73, v74, v75
	global_store_dwordx2 v[84:85], v[72:73], off offset:96
	v_pk_mul_f32 v[72:73], v[70:71], v[100:101] op_sel_hi:[0,1]
	v_pk_mul_f32 v[74:75], v[70:71], v[102:103] op_sel_hi:[0,1]
	v_cvt_pk_bf16_f32 v72, v72, v73
	v_cvt_pk_bf16_f32 v73, v74, v75
	v_pk_mul_f32 v[86:87], v[104:105], v[70:71] op_sel_hi:[1,0]
	v_pk_mul_f32 v[104:105], v[106:107], v[70:71] op_sel_hi:[1,0]
	global_store_dwordx2 v[84:85], v[72:73], off offset:128
	v_pk_mul_f32 v[72:73], v[70:71], v[92:93] op_sel_hi:[0,1]
	v_pk_mul_f32 v[74:75], v[70:71], v[94:95] op_sel_hi:[0,1]
	v_cvt_pk_bf16_f32 v86, v86, v87
	v_cvt_pk_bf16_f32 v87, v104, v105
	v_cvt_pk_bf16_f32 v72, v72, v73
	v_cvt_pk_bf16_f32 v73, v74, v75
	global_store_dwordx2 v[84:85], v[86:87], off
	v_pk_mul_f32 v[86:87], v[70:71], v[96:97] op_sel_hi:[0,1]
	v_pk_mul_f32 v[96:97], v[70:71], v[98:99] op_sel_hi:[0,1]
	global_store_dwordx2 v[84:85], v[72:73], off offset:160
	v_pk_mul_f32 v[72:73], v[70:71], v[80:81] op_sel_hi:[0,1]
	v_pk_mul_f32 v[74:75], v[70:71], v[82:83] op_sel_hi:[0,1]
	v_cvt_pk_bf16_f32 v86, v86, v87
	v_cvt_pk_bf16_f32 v87, v96, v97
	v_cvt_pk_bf16_f32 v72, v72, v73
	v_cvt_pk_bf16_f32 v73, v74, v75
	global_store_dwordx2 v[84:85], v[86:87], off offset:32
	v_pk_mul_f32 v[86:87], v[70:71], v[88:89] op_sel_hi:[0,1]
	v_pk_mul_f32 v[88:89], v[70:71], v[90:91] op_sel_hi:[0,1]
	global_store_dwordx2 v[84:85], v[72:73], off offset:192
	v_pk_mul_f32 v[72:73], v[70:71], v[76:77] op_sel_hi:[0,1]
	v_pk_mul_f32 v[70:71], v[70:71], v[78:79] op_sel_hi:[0,1]
	v_cvt_pk_bf16_f32 v86, v86, v87
	v_cvt_pk_bf16_f32 v87, v88, v89
	v_cvt_pk_bf16_f32 v72, v72, v73
	v_cvt_pk_bf16_f32 v73, v70, v71
	v_cmp_eq_u32_e32 vcc, 0, v116
	global_store_dwordx2 v[84:85], v[86:87], off offset:64
	global_store_dwordx2 v[84:85], v[72:73], off offset:224
	s_and_saveexec_b64 s[0:1], vcc
	s_cbranch_execz .LBB0_432
	v_log_f32_e32 v2, v68
	s_ashr_i32 s5, s4, 31
	s_lshl_b64 s[4:5], s[4:5], 19
	v_readlane_b32 s6, v251, 28
	v_readlane_b32 s7, v251, 29
	s_add_u32 s4, s6, s4
	s_addc_u32 s5, s7, s5
	v_lshlrev_b64 v[0:1], 5, v[0:1]
	v_add_f32_e32 v2, v69, v2
	v_lshl_add_u64 v[0:1], s[4:5], 0, v[0:1]
	s_lshl_b32 s18, s9, 2
	v_mul_f32_e32 v2, 0x3f317218, v2
	v_lshl_add_u64 v[0:1], v[0:1], 0, s[18:19]
	global_store_dword v[0:1], v2, off
	s_branch .LBB0_432
.Ldil_nopre:
	s_waitcnt vmcnt(0)
	s_branch .LBB0_457
